# DIFF item epilogue: fifteen gate loads prefetched behind the first group, counted vmcnt waits
# baseline (speedup 1.0000x reference)
; DI float xor32_sum(float v) { auto rr = __builtin_amdgcn_permlane32_swap(__float_as_uint(v), __float_as_uint(v), false, false); return __uint_as_float(rr[0]) + __uint_as_float(rr[1]); }
; template <bool DIFF>
; DI void attn_phase(const AttnArgs& a, char* lds) {
;     ...
;       if (comp == 0) {
;         float ss = 0.f;
; #pragma unroll
;         for (int m = 0; m < NM; ++m)
; #pragma unroll
;           for (int r = 0; r < 16; ++r) { const float d = o[m][r] * inv - ex[(m * 16 + r) * 64]; o[m][r] = d; ss += d * d; if (r == 15) asm volatile("" : "+v"(ss) :: "memory"); }
;         ss = xor32_sum(ss);
.LBB0_633:
	s_andn2_b64 vcc, exec, s[14:15]
	s_waitcnt lgkmcnt(0)
	s_barrier
	s_cbranch_vccnz .LBB0_587
	v_lshrrev_b32_e32 v152, 5, v4
	ds_read2st64_b32 v[4:5], v2 offset1:1
	ds_read2st64_b32 v[6:7], v2 offset0:2 offset1:3
	ds_read2st64_b32 v[8:9], v2 offset0:4 offset1:5
	ds_read2st64_b32 v[10:11], v2 offset0:6 offset1:7
	ds_read2st64_b32 v[12:13], v2 offset0:8 offset1:9
	ds_read2st64_b32 v[154:155], v2 offset0:10 offset1:11
	ds_read2st64_b32 v[156:157], v2 offset0:12 offset1:13
	ds_read2st64_b32 v[158:159], v2 offset0:14 offset1:15
	s_waitcnt lgkmcnt(7)
	v_pk_fma_f32 v[150:151], v[128:129], v[0:1], v[4:5] op_sel_hi:[1,0,1] neg_lo:[0,0,1] neg_hi:[0,0,1]
	v_and_or_b32 v3, v3, 31, s76
	v_lshl_or_b32 v14, v152, 3, s75
	s_waitcnt lgkmcnt(6)
	v_pk_fma_f32 v[148:149], v[130:131], v[0:1], v[6:7] op_sel_hi:[1,0,1] neg_lo:[0,0,1] neg_hi:[0,0,1]
	v_pk_mul_f32 v[4:5], v[150:151], v[150:151]
	v_lshl_add_u32 v14, v3, 11, v14
	v_pk_mul_f32 v[6:7], v[148:149], v[148:149]
	v_add_f32_e32 v3, v4, v5
	s_waitcnt lgkmcnt(5)
	v_pk_fma_f32 v[146:147], v[132:133], v[0:1], v[8:9] op_sel_hi:[1,0,1] neg_lo:[0,0,1] neg_hi:[0,0,1]
	v_add_f32_e32 v3, v3, v6
	v_pk_mul_f32 v[8:9], v[146:147], v[146:147]
	v_add_f32_e32 v3, v3, v7
	s_waitcnt lgkmcnt(4)
	v_pk_fma_f32 v[144:145], v[134:135], v[0:1], v[10:11] op_sel_hi:[1,0,1] neg_lo:[0,0,1] neg_hi:[0,0,1]
	v_add_f32_e32 v3, v3, v8
	v_pk_mul_f32 v[10:11], v[144:145], v[144:145]
	v_add_f32_e32 v3, v3, v9
	s_waitcnt lgkmcnt(3)
	v_pk_fma_f32 v[136:137], v[136:137], v[0:1], v[12:13] op_sel_hi:[1,0,1] neg_lo:[0,0,1] neg_hi:[0,0,1]
	v_add_f32_e32 v3, v3, v10
	v_pk_mul_f32 v[12:13], v[136:137], v[136:137]
	v_add_f32_e32 v3, v3, v11
	s_waitcnt lgkmcnt(2)
	v_pk_fma_f32 v[138:139], v[138:139], v[0:1], v[154:155] op_sel_hi:[1,0,1] neg_lo:[0,0,1] neg_hi:[0,0,1]
	v_add_f32_e32 v3, v3, v12
	v_pk_mul_f32 v[132:133], v[138:139], v[138:139]
	v_add_f32_e32 v3, v3, v13
	s_waitcnt lgkmcnt(1)
	v_pk_fma_f32 v[140:141], v[140:141], v[0:1], v[156:157] op_sel_hi:[1,0,1] neg_lo:[0,0,1] neg_hi:[0,0,1]
	v_add_f32_e32 v3, v3, v132
	v_pk_mul_f32 v[130:131], v[140:141], v[140:141]
	v_add_f32_e32 v3, v3, v133
	s_waitcnt lgkmcnt(0)
	v_pk_fma_f32 v[142:143], v[142:143], v[0:1], v[158:159] op_sel_hi:[1,0,1] neg_lo:[0,0,1] neg_hi:[0,0,1]
	v_add_f32_e32 v3, v3, v130
	v_pk_mul_f32 v[128:129], v[142:143], v[142:143]
	v_add_f32_e32 v3, v3, v131
	v_add_f32_e32 v3, v3, v128
	v_add_f32_e32 v3, v3, v129
	ds_read2st64_b32 v[4:5], v2 offset0:16 offset1:17
	ds_read2st64_b32 v[6:7], v2 offset0:18 offset1:19
	ds_read2st64_b32 v[8:9], v2 offset0:20 offset1:21
	ds_read2st64_b32 v[10:11], v2 offset0:22 offset1:23
	ds_read2st64_b32 v[12:13], v2 offset0:24 offset1:25
	ds_read2st64_b32 v[154:155], v2 offset0:26 offset1:27
	ds_read2st64_b32 v[156:157], v2 offset0:28 offset1:29
	ds_read2st64_b32 v[158:159], v2 offset0:30 offset1:31
	s_waitcnt lgkmcnt(7)
	v_pk_fma_f32 v[134:135], v[112:113], v[0:1], v[4:5] op_sel_hi:[1,0,1] neg_lo:[0,0,1] neg_hi:[0,0,1]
	s_waitcnt lgkmcnt(6)
	v_pk_fma_f32 v[132:133], v[114:115], v[0:1], v[6:7] op_sel_hi:[1,0,1] neg_lo:[0,0,1] neg_hi:[0,0,1]
	v_pk_mul_f32 v[4:5], v[134:135], v[134:135]
	v_pk_mul_f32 v[6:7], v[132:133], v[132:133]
	v_add_f32_e32 v3, v3, v4
	v_add_f32_e32 v3, v3, v5
	s_waitcnt lgkmcnt(5)
	v_pk_fma_f32 v[130:131], v[116:117], v[0:1], v[8:9] op_sel_hi:[1,0,1] neg_lo:[0,0,1] neg_hi:[0,0,1]
	v_add_f32_e32 v3, v3, v6
	v_pk_mul_f32 v[8:9], v[130:131], v[130:131]
	v_add_f32_e32 v3, v3, v7
	s_waitcnt lgkmcnt(4)
	v_pk_fma_f32 v[128:129], v[118:119], v[0:1], v[10:11] op_sel_hi:[1,0,1] neg_lo:[0,0,1] neg_hi:[0,0,1]
	v_add_f32_e32 v3, v3, v8
	v_pk_mul_f32 v[10:11], v[128:129], v[128:129]
	v_add_f32_e32 v3, v3, v9
	v_add_f32_e32 v3, v3, v10
	s_waitcnt lgkmcnt(3)
	v_pk_fma_f32 v[120:121], v[120:121], v[0:1], v[12:13] op_sel_hi:[1,0,1] neg_lo:[0,0,1] neg_hi:[0,0,1]
	v_add_f32_e32 v3, v3, v11
	v_pk_mul_f32 v[10:11], v[120:121], v[120:121]
	s_waitcnt lgkmcnt(2)
	v_pk_fma_f32 v[122:123], v[122:123], v[0:1], v[154:155] op_sel_hi:[1,0,1] neg_lo:[0,0,1] neg_hi:[0,0,1]
	v_add_f32_e32 v3, v3, v10
	v_pk_mul_f32 v[8:9], v[122:123], v[122:123]
	v_add_f32_e32 v3, v3, v11
	s_waitcnt lgkmcnt(1)
	v_pk_fma_f32 v[124:125], v[124:125], v[0:1], v[156:157] op_sel_hi:[1,0,1] neg_lo:[0,0,1] neg_hi:[0,0,1]
	v_add_f32_e32 v3, v3, v8
	v_pk_mul_f32 v[6:7], v[124:125], v[124:125]
	v_add_f32_e32 v3, v3, v9
	s_waitcnt lgkmcnt(0)
	v_pk_fma_f32 v[126:127], v[126:127], v[0:1], v[158:159] op_sel_hi:[1,0,1] neg_lo:[0,0,1] neg_hi:[0,0,1]
	v_add_f32_e32 v3, v3, v6
	v_pk_mul_f32 v[4:5], v[126:127], v[126:127]
	v_add_f32_e32 v3, v3, v7
	v_add_f32_e32 v3, v3, v4
	v_add_f32_e32 v3, v3, v5
	ds_read2st64_b32 v[4:5], v2 offset0:32 offset1:33
	ds_read2st64_b32 v[6:7], v2 offset0:34 offset1:35
	ds_read2st64_b32 v[8:9], v2 offset0:36 offset1:37
	ds_read2st64_b32 v[10:11], v2 offset0:38 offset1:39
	ds_read2st64_b32 v[12:13], v2 offset0:40 offset1:41
	ds_read2st64_b32 v[154:155], v2 offset0:42 offset1:43
	ds_read2st64_b32 v[156:157], v2 offset0:44 offset1:45
	ds_read2st64_b32 v[158:159], v2 offset0:46 offset1:47
	s_waitcnt lgkmcnt(7)
	v_pk_fma_f32 v[118:119], v[96:97], v[0:1], v[4:5] op_sel_hi:[1,0,1] neg_lo:[0,0,1] neg_hi:[0,0,1]
	s_waitcnt lgkmcnt(6)
	v_pk_fma_f32 v[116:117], v[98:99], v[0:1], v[6:7] op_sel_hi:[1,0,1] neg_lo:[0,0,1] neg_hi:[0,0,1]
	v_pk_mul_f32 v[4:5], v[118:119], v[118:119]
	v_pk_mul_f32 v[6:7], v[116:117], v[116:117]
	v_add_f32_e32 v3, v3, v4
	v_add_f32_e32 v3, v3, v5
	s_waitcnt lgkmcnt(5)
	v_pk_fma_f32 v[114:115], v[100:101], v[0:1], v[8:9] op_sel_hi:[1,0,1] neg_lo:[0,0,1] neg_hi:[0,0,1]
	v_add_f32_e32 v3, v3, v6
	v_pk_mul_f32 v[8:9], v[114:115], v[114:115]
	v_add_f32_e32 v3, v3, v7
	s_waitcnt lgkmcnt(4)
; template <bool DIFF>
; DI void attn_phase(const AttnArgs& a, char* lds) {
;     ...
;       if (comp == 0) {
;         float ss = 0.f;
; #pragma unroll
;         for (int m = 0; m < NM; ++m)
; #pragma unroll
;           for (int r = 0; r < 16; ++r) { const float d = o[m][r] * inv - ex[(m * 16 + r) * 64]; o[m][r] = d; ss += d * d; if (r == 15) asm volatile("" : "+v"(ss) :: "memory"); }
	v_pk_fma_f32 v[112:113], v[102:103], v[0:1], v[10:11] op_sel_hi:[1,0,1] neg_lo:[0,0,1] neg_hi:[0,0,1]
	v_add_f32_e32 v3, v3, v8
	v_pk_mul_f32 v[10:11], v[112:113], v[112:113]
	v_add_f32_e32 v3, v3, v9
	v_add_f32_e32 v3, v3, v10
	s_waitcnt lgkmcnt(3)
	v_pk_fma_f32 v[104:105], v[104:105], v[0:1], v[12:13] op_sel_hi:[1,0,1] neg_lo:[0,0,1] neg_hi:[0,0,1]
	v_add_f32_e32 v3, v3, v11
	v_pk_mul_f32 v[10:11], v[104:105], v[104:105]
	s_waitcnt lgkmcnt(2)
	v_pk_fma_f32 v[106:107], v[106:107], v[0:1], v[154:155] op_sel_hi:[1,0,1] neg_lo:[0,0,1] neg_hi:[0,0,1]
	v_add_f32_e32 v3, v3, v10
	v_pk_mul_f32 v[8:9], v[106:107], v[106:107]
	v_add_f32_e32 v3, v3, v11
	s_waitcnt lgkmcnt(1)
	v_pk_fma_f32 v[108:109], v[108:109], v[0:1], v[156:157] op_sel_hi:[1,0,1] neg_lo:[0,0,1] neg_hi:[0,0,1]
	v_add_f32_e32 v3, v3, v8
	v_pk_mul_f32 v[6:7], v[108:109], v[108:109]
	v_add_f32_e32 v3, v3, v9
	s_waitcnt lgkmcnt(0)
	v_pk_fma_f32 v[110:111], v[110:111], v[0:1], v[158:159] op_sel_hi:[1,0,1] neg_lo:[0,0,1] neg_hi:[0,0,1]
	v_add_f32_e32 v3, v3, v6
	v_pk_mul_f32 v[4:5], v[110:111], v[110:111]
	v_add_f32_e32 v3, v3, v7
	v_add_f32_e32 v3, v3, v4
	v_add_f32_e32 v3, v3, v5
	ds_read2st64_b32 v[4:5], v2 offset0:48 offset1:49
	ds_read2st64_b32 v[6:7], v2 offset0:50 offset1:51
	ds_read2st64_b32 v[8:9], v2 offset0:52 offset1:53
	ds_read2st64_b32 v[10:11], v2 offset0:54 offset1:55
	ds_read2st64_b32 v[12:13], v2 offset0:56 offset1:57
	ds_read2st64_b32 v[154:155], v2 offset0:58 offset1:59
	ds_read2st64_b32 v[156:157], v2 offset0:60 offset1:61
	ds_read2st64_b32 v[158:159], v2 offset0:62 offset1:63
	s_waitcnt lgkmcnt(7)
	v_pk_fma_f32 v[102:103], v[80:81], v[0:1], v[4:5] op_sel_hi:[1,0,1] neg_lo:[0,0,1] neg_hi:[0,0,1]
	s_waitcnt lgkmcnt(6)
	v_pk_fma_f32 v[100:101], v[82:83], v[0:1], v[6:7] op_sel_hi:[1,0,1] neg_lo:[0,0,1] neg_hi:[0,0,1]
	v_pk_mul_f32 v[4:5], v[102:103], v[102:103]
	v_pk_mul_f32 v[6:7], v[100:101], v[100:101]
	v_add_f32_e32 v3, v3, v4
	v_add_f32_e32 v3, v3, v5
	s_waitcnt lgkmcnt(5)
	v_pk_fma_f32 v[98:99], v[84:85], v[0:1], v[8:9] op_sel_hi:[1,0,1] neg_lo:[0,0,1] neg_hi:[0,0,1]
	v_add_f32_e32 v3, v3, v6
	v_pk_mul_f32 v[8:9], v[98:99], v[98:99]
	v_add_f32_e32 v3, v3, v7
	s_waitcnt lgkmcnt(4)
	v_pk_fma_f32 v[96:97], v[86:87], v[0:1], v[10:11] op_sel_hi:[1,0,1] neg_lo:[0,0,1] neg_hi:[0,0,1]
	v_add_f32_e32 v3, v3, v8
	v_pk_mul_f32 v[10:11], v[96:97], v[96:97]
	v_add_f32_e32 v3, v3, v9
	v_add_f32_e32 v3, v3, v10
	s_waitcnt lgkmcnt(3)
	v_pk_fma_f32 v[88:89], v[88:89], v[0:1], v[12:13] op_sel_hi:[1,0,1] neg_lo:[0,0,1] neg_hi:[0,0,1]
	v_add_f32_e32 v3, v3, v11
	v_pk_mul_f32 v[10:11], v[88:89], v[88:89]
	s_waitcnt lgkmcnt(2)
	v_pk_fma_f32 v[90:91], v[90:91], v[0:1], v[154:155] op_sel_hi:[1,0,1] neg_lo:[0,0,1] neg_hi:[0,0,1]
	v_add_f32_e32 v3, v3, v10
	v_pk_mul_f32 v[8:9], v[90:91], v[90:91]
	v_add_f32_e32 v3, v3, v11
	s_waitcnt lgkmcnt(1)
	v_pk_fma_f32 v[92:93], v[92:93], v[0:1], v[156:157] op_sel_hi:[1,0,1] neg_lo:[0,0,1] neg_hi:[0,0,1]
	v_add_f32_e32 v3, v3, v8
	v_pk_mul_f32 v[6:7], v[92:93], v[92:93]
	v_add_f32_e32 v3, v3, v9
	s_waitcnt lgkmcnt(0)
	v_pk_fma_f32 v[94:95], v[94:95], v[0:1], v[158:159] op_sel_hi:[1,0,1] neg_lo:[0,0,1] neg_hi:[0,0,1]
	v_add_f32_e32 v3, v3, v6
	v_pk_mul_f32 v[4:5], v[94:95], v[94:95]
	v_add_f32_e32 v3, v3, v7
	v_add_f32_e32 v3, v3, v4
	v_add_f32_e32 v3, v3, v5
	ds_read2st64_b32 v[4:5], v2 offset0:64 offset1:65
	ds_read2st64_b32 v[6:7], v2 offset0:66 offset1:67
	ds_read2st64_b32 v[8:9], v2 offset0:68 offset1:69
	ds_read2st64_b32 v[10:11], v2 offset0:70 offset1:71
	ds_read2st64_b32 v[12:13], v2 offset0:72 offset1:73
	ds_read2st64_b32 v[154:155], v2 offset0:74 offset1:75
	ds_read2st64_b32 v[156:157], v2 offset0:76 offset1:77
	ds_read2st64_b32 v[158:159], v2 offset0:78 offset1:79
	s_waitcnt lgkmcnt(7)
	v_pk_fma_f32 v[86:87], v[64:65], v[0:1], v[4:5] op_sel_hi:[1,0,1] neg_lo:[0,0,1] neg_hi:[0,0,1]
	s_waitcnt lgkmcnt(6)
	v_pk_fma_f32 v[84:85], v[66:67], v[0:1], v[6:7] op_sel_hi:[1,0,1] neg_lo:[0,0,1] neg_hi:[0,0,1]
	v_pk_mul_f32 v[4:5], v[86:87], v[86:87]
	v_pk_mul_f32 v[6:7], v[84:85], v[84:85]
	v_add_f32_e32 v3, v3, v4
	v_add_f32_e32 v3, v3, v5
	s_waitcnt lgkmcnt(5)
	v_pk_fma_f32 v[82:83], v[68:69], v[0:1], v[8:9] op_sel_hi:[1,0,1] neg_lo:[0,0,1] neg_hi:[0,0,1]
	v_add_f32_e32 v3, v3, v6
	v_pk_mul_f32 v[8:9], v[82:83], v[82:83]
	v_add_f32_e32 v3, v3, v7
	s_waitcnt lgkmcnt(4)
	v_pk_fma_f32 v[80:81], v[70:71], v[0:1], v[10:11] op_sel_hi:[1,0,1] neg_lo:[0,0,1] neg_hi:[0,0,1]
	v_add_f32_e32 v3, v3, v8
	v_pk_mul_f32 v[10:11], v[80:81], v[80:81]
	v_add_f32_e32 v3, v3, v9
	v_add_f32_e32 v3, v3, v10
	s_waitcnt lgkmcnt(3)
	v_pk_fma_f32 v[72:73], v[72:73], v[0:1], v[12:13] op_sel_hi:[1,0,1] neg_lo:[0,0,1] neg_hi:[0,0,1]
	v_add_f32_e32 v3, v3, v11
	v_pk_mul_f32 v[10:11], v[72:73], v[72:73]
	s_waitcnt lgkmcnt(2)
	v_pk_fma_f32 v[74:75], v[74:75], v[0:1], v[154:155] op_sel_hi:[1,0,1] neg_lo:[0,0,1] neg_hi:[0,0,1]
	v_add_f32_e32 v3, v3, v10
	v_pk_mul_f32 v[8:9], v[74:75], v[74:75]
	v_add_f32_e32 v3, v3, v11
	s_waitcnt lgkmcnt(1)
	v_pk_fma_f32 v[76:77], v[76:77], v[0:1], v[156:157] op_sel_hi:[1,0,1] neg_lo:[0,0,1] neg_hi:[0,0,1]
	v_add_f32_e32 v3, v3, v8
	v_pk_mul_f32 v[6:7], v[76:77], v[76:77]
	v_add_f32_e32 v3, v3, v9
	s_waitcnt lgkmcnt(0)
	v_pk_fma_f32 v[78:79], v[78:79], v[0:1], v[158:159] op_sel_hi:[1,0,1] neg_lo:[0,0,1] neg_hi:[0,0,1]
	v_add_f32_e32 v3, v3, v6
	v_pk_mul_f32 v[4:5], v[78:79], v[78:79]
	v_add_f32_e32 v3, v3, v7
	v_add_f32_e32 v3, v3, v4
	v_add_f32_e32 v3, v3, v5
	ds_read2st64_b32 v[4:5], v2 offset0:80 offset1:81
	ds_read2st64_b32 v[6:7], v2 offset0:82 offset1:83
	ds_read2st64_b32 v[8:9], v2 offset0:84 offset1:85
	ds_read2st64_b32 v[10:11], v2 offset0:86 offset1:87
	ds_read2st64_b32 v[12:13], v2 offset0:88 offset1:89
	ds_read2st64_b32 v[154:155], v2 offset0:90 offset1:91
	ds_read2st64_b32 v[156:157], v2 offset0:92 offset1:93
	ds_read2st64_b32 v[158:159], v2 offset0:94 offset1:95
	s_waitcnt lgkmcnt(7)
; template <bool DIFF>
; DI void attn_phase(const AttnArgs& a, char* lds) {
;     ...
;       if (comp == 0) {
;         float ss = 0.f;
; #pragma unroll
;         for (int m = 0; m < NM; ++m)
; #pragma unroll
;           for (int r = 0; r < 16; ++r) { const float d = o[m][r] * inv - ex[(m * 16 + r) * 64]; o[m][r] = d; ss += d * d; if (r == 15) asm volatile("" : "+v"(ss) :: "memory"); }
	v_pk_fma_f32 v[70:71], v[48:49], v[0:1], v[4:5] op_sel_hi:[1,0,1] neg_lo:[0,0,1] neg_hi:[0,0,1]
	s_waitcnt lgkmcnt(6)
	v_pk_fma_f32 v[68:69], v[50:51], v[0:1], v[6:7] op_sel_hi:[1,0,1] neg_lo:[0,0,1] neg_hi:[0,0,1]
	v_pk_mul_f32 v[4:5], v[70:71], v[70:71]
	v_pk_mul_f32 v[6:7], v[68:69], v[68:69]
	v_add_f32_e32 v3, v3, v4
	v_add_f32_e32 v3, v3, v5
	s_waitcnt lgkmcnt(5)
	v_pk_fma_f32 v[66:67], v[52:53], v[0:1], v[8:9] op_sel_hi:[1,0,1] neg_lo:[0,0,1] neg_hi:[0,0,1]
	v_add_f32_e32 v3, v3, v6
	v_pk_mul_f32 v[8:9], v[66:67], v[66:67]
	v_add_f32_e32 v3, v3, v7
	s_waitcnt lgkmcnt(4)
	v_pk_fma_f32 v[64:65], v[54:55], v[0:1], v[10:11] op_sel_hi:[1,0,1] neg_lo:[0,0,1] neg_hi:[0,0,1]
	v_add_f32_e32 v3, v3, v8
	v_pk_mul_f32 v[10:11], v[64:65], v[64:65]
	v_add_f32_e32 v3, v3, v9
	v_add_f32_e32 v3, v3, v10
	s_waitcnt lgkmcnt(3)
	v_pk_fma_f32 v[56:57], v[56:57], v[0:1], v[12:13] op_sel_hi:[1,0,1] neg_lo:[0,0,1] neg_hi:[0,0,1]
	v_add_f32_e32 v3, v3, v11
	v_pk_mul_f32 v[10:11], v[56:57], v[56:57]
	s_waitcnt lgkmcnt(2)
	v_pk_fma_f32 v[58:59], v[58:59], v[0:1], v[154:155] op_sel_hi:[1,0,1] neg_lo:[0,0,1] neg_hi:[0,0,1]
	v_add_f32_e32 v3, v3, v10
	v_pk_mul_f32 v[8:9], v[58:59], v[58:59]
	v_add_f32_e32 v3, v3, v11
	s_waitcnt lgkmcnt(1)
	v_pk_fma_f32 v[60:61], v[60:61], v[0:1], v[156:157] op_sel_hi:[1,0,1] neg_lo:[0,0,1] neg_hi:[0,0,1]
	v_add_f32_e32 v3, v3, v8
	v_pk_mul_f32 v[6:7], v[60:61], v[60:61]
	v_add_f32_e32 v3, v3, v9
	s_waitcnt lgkmcnt(0)
	v_pk_fma_f32 v[62:63], v[62:63], v[0:1], v[158:159] op_sel_hi:[1,0,1] neg_lo:[0,0,1] neg_hi:[0,0,1]
	v_add_f32_e32 v3, v3, v6
	v_pk_mul_f32 v[4:5], v[62:63], v[62:63]
	v_add_f32_e32 v3, v3, v7
	v_add_f32_e32 v3, v3, v4
	v_add_f32_e32 v3, v3, v5
	ds_read2st64_b32 v[4:5], v2 offset0:96 offset1:97
	ds_read2st64_b32 v[6:7], v2 offset0:98 offset1:99
	ds_read2st64_b32 v[8:9], v2 offset0:100 offset1:101
	ds_read2st64_b32 v[10:11], v2 offset0:102 offset1:103
	ds_read2st64_b32 v[12:13], v2 offset0:104 offset1:105
	ds_read2st64_b32 v[154:155], v2 offset0:106 offset1:107
	ds_read2st64_b32 v[156:157], v2 offset0:108 offset1:109
	ds_read2st64_b32 v[158:159], v2 offset0:110 offset1:111
	s_waitcnt lgkmcnt(7)
	v_pk_fma_f32 v[54:55], v[32:33], v[0:1], v[4:5] op_sel_hi:[1,0,1] neg_lo:[0,0,1] neg_hi:[0,0,1]
	s_waitcnt lgkmcnt(6)
	v_pk_fma_f32 v[52:53], v[34:35], v[0:1], v[6:7] op_sel_hi:[1,0,1] neg_lo:[0,0,1] neg_hi:[0,0,1]
	v_pk_mul_f32 v[4:5], v[54:55], v[54:55]
	v_pk_mul_f32 v[6:7], v[52:53], v[52:53]
	v_add_f32_e32 v3, v3, v4
	v_add_f32_e32 v3, v3, v5
	s_waitcnt lgkmcnt(5)
	v_pk_fma_f32 v[50:51], v[36:37], v[0:1], v[8:9] op_sel_hi:[1,0,1] neg_lo:[0,0,1] neg_hi:[0,0,1]
	v_add_f32_e32 v3, v3, v6
	v_pk_mul_f32 v[8:9], v[50:51], v[50:51]
	v_add_f32_e32 v3, v3, v7
	s_waitcnt lgkmcnt(4)
	v_pk_fma_f32 v[48:49], v[38:39], v[0:1], v[10:11] op_sel_hi:[1,0,1] neg_lo:[0,0,1] neg_hi:[0,0,1]
	v_add_f32_e32 v3, v3, v8
	v_pk_mul_f32 v[10:11], v[48:49], v[48:49]
	v_add_f32_e32 v3, v3, v9
	v_add_f32_e32 v3, v3, v10
	s_waitcnt lgkmcnt(3)
	v_pk_fma_f32 v[38:39], v[40:41], v[0:1], v[12:13] op_sel_hi:[1,0,1] neg_lo:[0,0,1] neg_hi:[0,0,1]
	v_add_f32_e32 v3, v3, v11
	v_pk_mul_f32 v[10:11], v[38:39], v[38:39]
	s_waitcnt lgkmcnt(2)
	v_pk_fma_f32 v[36:37], v[42:43], v[0:1], v[154:155] op_sel_hi:[1,0,1] neg_lo:[0,0,1] neg_hi:[0,0,1]
	v_add_f32_e32 v3, v3, v10
	v_pk_mul_f32 v[8:9], v[36:37], v[36:37]
	v_add_f32_e32 v3, v3, v11
	s_waitcnt lgkmcnt(1)
	v_pk_fma_f32 v[34:35], v[44:45], v[0:1], v[156:157] op_sel_hi:[1,0,1] neg_lo:[0,0,1] neg_hi:[0,0,1]
	v_add_f32_e32 v3, v3, v8
	v_pk_mul_f32 v[6:7], v[34:35], v[34:35]
	v_add_f32_e32 v3, v3, v9
	s_waitcnt lgkmcnt(0)
	v_pk_fma_f32 v[32:33], v[46:47], v[0:1], v[158:159] op_sel_hi:[1,0,1] neg_lo:[0,0,1] neg_hi:[0,0,1]
	v_add_f32_e32 v3, v3, v6
	v_pk_mul_f32 v[4:5], v[32:33], v[32:33]
	v_add_f32_e32 v3, v3, v7
	v_add_f32_e32 v3, v3, v4
	v_add_f32_e32 v44, v3, v5
	ds_read2st64_b32 v[4:5], v2 offset0:112 offset1:113
	ds_read2st64_b32 v[6:7], v2 offset0:114 offset1:115
	ds_read2st64_b32 v[8:9], v2 offset0:116 offset1:117
	ds_read2st64_b32 v[10:11], v2 offset0:118 offset1:119
	ds_read2st64_b32 v[12:13], v2 offset0:120 offset1:121
	ds_read2st64_b32 v[40:41], v2 offset0:122 offset1:123
	ds_read2st64_b32 v[42:43], v2 offset0:124 offset1:125
	ds_read2st64_b32 v[2:3], v2 offset0:126 offset1:127
	s_waitcnt lgkmcnt(7)
	v_pk_fma_f32 v[16:17], v[16:17], v[0:1], v[4:5] op_sel_hi:[1,0,1] neg_lo:[0,0,1] neg_hi:[0,0,1]
	s_waitcnt lgkmcnt(6)
	v_pk_fma_f32 v[18:19], v[18:19], v[0:1], v[6:7] op_sel_hi:[1,0,1] neg_lo:[0,0,1] neg_hi:[0,0,1]
	v_pk_mul_f32 v[4:5], v[16:17], v[16:17]
	v_pk_mul_f32 v[6:7], v[18:19], v[18:19]
	v_add_f32_e32 v4, v44, v4
	v_add_f32_e32 v4, v4, v5
	s_waitcnt lgkmcnt(5)
	v_pk_fma_f32 v[20:21], v[20:21], v[0:1], v[8:9] op_sel_hi:[1,0,1] neg_lo:[0,0,1] neg_hi:[0,0,1]
	v_add_f32_e32 v4, v4, v6
	v_pk_mul_f32 v[8:9], v[20:21], v[20:21]
	v_add_f32_e32 v4, v4, v7
	s_waitcnt lgkmcnt(4)
	v_pk_fma_f32 v[10:11], v[22:23], v[0:1], v[10:11] op_sel_hi:[1,0,1] neg_lo:[0,0,1] neg_hi:[0,0,1]
	v_add_f32_e32 v4, v4, v8
	v_pk_mul_f32 v[22:23], v[10:11], v[10:11]
	v_add_f32_e32 v4, v4, v9
	v_add_f32_e32 v4, v4, v22
	s_waitcnt lgkmcnt(3)
	v_pk_fma_f32 v[8:9], v[24:25], v[0:1], v[12:13] op_sel_hi:[1,0,1] neg_lo:[0,0,1] neg_hi:[0,0,1]
	v_add_f32_e32 v44, v4, v23
	v_pk_mul_f32 v[12:13], v[8:9], v[8:9]
	s_waitcnt lgkmcnt(0)
; DI float bflo(u32 u) { return __uint_as_float(u << 16); }
; template <bool DIFF>
; DI void attn_phase(const AttnArgs& a, char* lds) {
;     ...
;           for (int r = 0; r < 16; ++r) { const float d = o[m][r] * inv - ex[(m * 16 + r) * 64]; o[m][r] = d; ss += d * d; if (r == 15) asm volatile("" : "+v"(ss) :: "memory"); }
;         ss = xor32_sum(ss);
;         const float rn = rsqrtf(ss * (1.0f / 256.0f) + EPS) * (1.0f - lam_init);
;         u32 go2 = (u32)qrow * (u32)a.ldg + (u32)(a.goff + h * 256 + 8 * g); pinu(go2);
;         u32 oo2 = (u32)qrow * 2048u + (u32)(h * 256 + 8 * g); pinu(oo2);
; #pragma unroll
;         for (int m = 0; m < NM; ++m)
; #pragma unroll
;           for (int bp = 0; bp < 2; ++bp) {
;             u32x2 pk[2];
;             const u32x4 gl = *(const u32x4*)(a.gate + go2 + 32 * m + 16 * bp);
;             const auto q0 = __builtin_amdgcn_permlane32_swap(gl[0], gl[2], false, false);
;             const auto q1 = __builtin_amdgcn_permlane32_swap(gl[1], gl[3], false, false);
;             u32x2 gsel[2]; gsel[0][0] = q0[0]; gsel[0][1] = q1[0]; gsel[1][0] = q0[1]; gsel[1][1] = q1[1];
; #pragma unroll
;             for (int bb = 0; bb < 2; ++bb) {
;               const int b = 2 * bp + bb;
;               const int dv = 32 * m + 8 * b;
;               const u32x2 gu = gsel[bb];
;               const float4 sg = *(const float4*)(a.subln + dv + 4 * g);
;               const float g0 = bflo(gu[0]), g1 = bfhi(gu[0]), g2 = bflo(gu[1]), g3 = bfhi(gu[1]);
;               const float y0 = o[m][4 * b] * rn * sg.x * g0 * __builtin_amdgcn_rcpf(1.f + __expf(-g0));
;               const float y1 = o[m][4 * b + 1] * rn * sg.y * g1 * __builtin_amdgcn_rcpf(1.f + __expf(-g1));
;               const float y2 = o[m][4 * b + 2] * rn * sg.z * g2 * __builtin_amdgcn_rcpf(1.f + __expf(-g2));
;               const float y3 = o[m][4 * b + 3] * rn * sg.w * g3 * __builtin_amdgcn_rcpf(1.f + __expf(-g3));
;               pk[bb][0] = pk2(y0, y1); pk[bb][1] = pk2(y2, y3);
;             }
;             const auto r0 = __builtin_amdgcn_permlane32_swap(pk[0][0], pk[1][0], false, false);
;             const auto r1 = __builtin_amdgcn_permlane32_swap(pk[0][1], pk[1][1], false, false);
;             u32x4 w; w[0] = r0[0]; w[1] = r1[0]; w[2] = r0[1]; w[3] = r1[1];
;             *(u32x4*)(a.og + oo2 + 32 * m + 16 * bp) = w;
;             __builtin_amdgcn_sched_barrier(0);
;           }
	v_pk_fma_f32 v[2:3], v[30:31], v[0:1], v[2:3] op_sel_hi:[1,0,1] neg_lo:[0,0,1] neg_hi:[0,0,1]
	v_pk_fma_f32 v[4:5], v[28:29], v[0:1], v[42:43] op_sel_hi:[1,0,1] neg_lo:[0,0,1] neg_hi:[0,0,1]
	v_pk_fma_f32 v[6:7], v[26:27], v[0:1], v[40:41] op_sel_hi:[1,0,1] neg_lo:[0,0,1] neg_hi:[0,0,1]
	v_add_f32_e32 v0, v44, v12
	v_pk_mul_f32 v[26:27], v[6:7], v[6:7]
	v_add_f32_e32 v0, v0, v13
	v_add_f32_e32 v0, v0, v26
	v_pk_mul_f32 v[28:29], v[4:5], v[4:5]
	v_add_f32_e32 v0, v0, v27
	v_add_f32_e32 v0, v0, v28
	v_pk_mul_f32 v[22:23], v[2:3], v[2:3]
	v_add_f32_e32 v0, v0, v29
	v_add_f32_e32 v0, v0, v22
	v_add_f32_e32 v23, v0, v23
	v_mov_b32_e32 v0, v14
	v_lshlrev_b32_e32 v22, 4, v152
	v_lshl_add_u64 v[12:13], v[0:1], 1, s[40:41]
	global_load_dwordx4 v[24:27], v[12:13], off
	global_load_dwordx4 v[28:31], v22, s[46:47]
	global_load_dwordx4 v[40:43], v22, s[46:47] offset:32
	global_load_dwordx4 v[160:163], v[12:13], off offset:32
	global_load_dwordx4 v[164:167], v[12:13], off offset:64
	global_load_dwordx4 v[168:171], v[12:13], off offset:96
	global_load_dwordx4 v[172:175], v[12:13], off offset:128
	global_load_dwordx4 v[176:179], v[12:13], off offset:160
	global_load_dwordx4 v[180:183], v[12:13], off offset:192
	global_load_dwordx4 v[184:187], v[12:13], off offset:224
	global_load_dwordx4 v[188:191], v[12:13], off offset:256
	global_load_dwordx4 v[192:195], v[12:13], off offset:288
	global_load_dwordx4 v[196:199], v[12:13], off offset:320
	global_load_dwordx4 v[200:203], v[12:13], off offset:352
	global_load_dwordx4 v[204:207], v[12:13], off offset:384
	global_load_dwordx4 v[228:231], v[12:13], off offset:416
	global_load_dwordx4 v[232:235], v[12:13], off offset:448
	global_load_dwordx4 v[236:239], v[12:13], off offset:480
	v_mov_b32_e32 v0, v23
	s_nop 1
	v_permlane32_swap_b32_e32 v23, v0
	v_add_f32_e32 v0, v23, v0
	v_fmamk_f32 v0, v0, 0x3b800000, v212
	v_mul_f32_e32 v23, 0x4b800000, v0
	v_cmp_gt_f32_e32 vcc, s72, v0
	s_waitcnt vmcnt(18)
	v_sub_f32_e32 v15, 1.0, v15
	s_waitcnt vmcnt(17)
	v_mov_b32_e32 v152, v27
	v_cndmask_b32_e32 v0, v0, v23, vcc
	v_rsq_f32_e32 v0, v0
	v_permlane32_swap_b32_e32 v25, v152
	v_mul_f32_e32 v23, 0x45800000, v0
	v_cndmask_b32_e32 v0, v0, v23, vcc
	v_mov_b32_e32 v23, v26
	s_nop 1
	v_permlane32_swap_b32_e32 v24, v23
	v_lshlrev_b32_e32 v26, 16, v24
	v_mul_f32_e32 v27, 0xbfb8aa3b, v26
	v_exp_f32_e32 v44, v27
	v_and_b32_e32 v27, 0xffff0000, v24
	v_mul_f32_e32 v45, 0xbfb8aa3b, v27
	v_exp_f32_e32 v45, v45
	v_mul_f32_e32 v0, v15, v0
	v_pk_mul_f32 v[46:47], v[150:151], v[0:1] op_sel_hi:[1,0]
	v_lshlrev_b32_e32 v24, 16, v25
	s_waitcnt vmcnt(16)
	v_pk_mul_f32 v[28:29], v[28:29], v[46:47]
	v_and_b32_e32 v25, 0xffff0000, v25
	v_pk_mul_f32 v[26:27], v[28:29], v[26:27]
	v_add_f32_e32 v28, 1.0, v45
	v_rcp_f32_e32 v45, v28
	v_mul_f32_e32 v28, 0xbfb8aa3b, v24
	v_mul_f32_e32 v29, 0xbfb8aa3b, v25
	v_exp_f32_e32 v28, v28
	v_exp_f32_e32 v29, v29
	v_add_f32_e32 v44, 1.0, v44
	v_rcp_f32_e32 v44, v44
	v_add_f32_e32 v28, 1.0, v28
	v_add_f32_e32 v29, 1.0, v29
	v_rcp_f32_e32 v28, v28
	v_rcp_f32_e32 v29, v29
	v_pk_mul_f32 v[26:27], v[44:45], v[26:27]
	v_pk_mul_f32 v[44:45], v[148:149], v[0:1] op_sel_hi:[1,0]
	v_mov_b32_e32 v15, v1
	v_pk_mul_f32 v[30:31], v[30:31], v[44:45]
	v_pk_mul_f32 v[44:45], v[146:147], v[0:1] op_sel_hi:[1,0]
	v_pk_mul_f32 v[24:25], v[30:31], v[24:25]
	s_waitcnt vmcnt(15)
	v_pk_mul_f32 v[40:41], v[40:41], v[44:45]
	v_pk_mul_f32 v[28:29], v[28:29], v[24:25]
	v_cvt_pk_bf16_f32 v24, v26, v27
	v_lshlrev_b32_e32 v26, 16, v23
	v_mul_f32_e32 v27, 0xbfb8aa3b, v26
	v_exp_f32_e32 v30, v27
	v_and_b32_e32 v27, 0xffff0000, v23
	v_cvt_pk_bf16_f32 v25, v28, v29
	v_lshlrev_b32_e32 v28, 16, v152
	v_add_f32_e32 v23, 1.0, v30
	v_rcp_f32_e32 v30, v23
	v_mul_f32_e32 v23, 0xbfb8aa3b, v27
	v_exp_f32_e32 v23, v23
	v_and_b32_e32 v29, 0xffff0000, v152
	v_pk_mul_f32 v[26:27], v[40:41], v[26:27]
	v_mul_f32_e32 v40, 0xbfb8aa3b, v29
	v_add_f32_e32 v23, 1.0, v23
	v_rcp_f32_e32 v31, v23
	v_mul_f32_e32 v23, 0xbfb8aa3b, v28
	v_exp_f32_e32 v23, v23
	v_exp_f32_e32 v40, v40
	v_pk_mul_f32 v[26:27], v[30:31], v[26:27]
	v_lshl_add_u64 v[14:15], v[14:15], 1, s[24:25]
	v_add_f32_e32 v23, 1.0, v23
	v_rcp_f32_e32 v30, v23
	v_add_f32_e32 v23, 1.0, v40
	v_rcp_f32_e32 v31, v23
	v_pk_mul_f32 v[40:41], v[144:145], v[0:1] op_sel_hi:[1,0]
	v_cvt_pk_bf16_f32 v26, v26, v27
	v_pk_mul_f32 v[40:41], v[42:43], v[40:41]
	s_nop 0
	v_permlane32_swap_b32_e32 v24, v26
	v_pk_mul_f32 v[28:29], v[40:41], v[28:29]
	s_nop 0
	v_pk_mul_f32 v[28:29], v[30:31], v[28:29]
	s_nop 0
	v_cvt_pk_bf16_f32 v27, v28, v29
	s_nop 1
	v_permlane32_swap_b32_e32 v25, v27
	global_store_dwordx4 v[14:15], v[24:27], off
	s_nop 0
	global_load_dwordx4 v[28:31], v22, s[46:47] offset:64
	global_load_dwordx4 v[40:43], v22, s[46:47] offset:96
	s_waitcnt vmcnt(17)
	v_mov_b32_e32 v24, v160
	v_mov_b32_e32 v25, v161
	v_mov_b32_e32 v26, v162
	v_mov_b32_e32 v27, v163
	v_pk_mul_f32 v[44:45], v[136:137], v[0:1] op_sel_hi:[1,0]
	v_pk_mul_f32 v[136:137], v[140:141], v[0:1] op_sel_hi:[1,0]
	v_pk_mul_f32 v[46:47], v[138:139], v[0:1] op_sel_hi:[1,0]
	v_pk_mul_f32 v[138:139], v[142:143], v[0:1] op_sel_hi:[1,0]
	s_waitcnt vmcnt(2)
	v_mov_b32_e32 v23, v26
	v_mov_b32_e32 v140, v27
	s_nop 0
	v_permlane32_swap_b32_e32 v24, v23
	v_permlane32_swap_b32_e32 v25, v140
	s_waitcnt vmcnt(1)
	v_pk_mul_f32 v[26:27], v[44:45], v[28:29]
	v_pk_mul_f32 v[28:29], v[46:47], v[30:31]
	s_waitcnt vmcnt(0)
; DI u32 pk2(float a, float b) { f2_t v = {a, b}; bf2_t r = __builtin_convertvector(v, bf2_t); return __builtin_bit_cast(u32, r); }
; DI float bflo(u32 u) { return __uint_as_float(u << 16); }
; DI float bfhi(u32 u) { return __uint_as_float(u & 0xffff0000u); }
; template <bool DIFF>
; DI void attn_phase(const AttnArgs& a, char* lds) {
;     ...
; #pragma unroll
;         for (int m = 0; m < NM; ++m)
; #pragma unroll
;           for (int bp = 0; bp < 2; ++bp) {
;             u32x2 pk[2];
;             const u32x4 gl = *(const u32x4*)(a.gate + go2 + 32 * m + 16 * bp);
;             const auto q0 = __builtin_amdgcn_permlane32_swap(gl[0], gl[2], false, false);
;             const auto q1 = __builtin_amdgcn_permlane32_swap(gl[1], gl[3], false, false);
;             u32x2 gsel[2]; gsel[0][0] = q0[0]; gsel[0][1] = q1[0]; gsel[1][0] = q0[1]; gsel[1][1] = q1[1];
; #pragma unroll
;             for (int bb = 0; bb < 2; ++bb) {
;               const int b = 2 * bp + bb;
;               const int dv = 32 * m + 8 * b;
;               const u32x2 gu = gsel[bb];
;               const float4 sg = *(const float4*)(a.subln + dv + 4 * g);
;               const float g0 = bflo(gu[0]), g1 = bfhi(gu[0]), g2 = bflo(gu[1]), g3 = bfhi(gu[1]);
;               const float y0 = o[m][4 * b] * rn * sg.x * g0 * __builtin_amdgcn_rcpf(1.f + __expf(-g0));
;               const float y1 = o[m][4 * b + 1] * rn * sg.y * g1 * __builtin_amdgcn_rcpf(1.f + __expf(-g1));
;               const float y2 = o[m][4 * b + 2] * rn * sg.z * g2 * __builtin_amdgcn_rcpf(1.f + __expf(-g2));
;               const float y3 = o[m][4 * b + 3] * rn * sg.w * g3 * __builtin_amdgcn_rcpf(1.f + __expf(-g3));
;               pk[bb][0] = pk2(y0, y1); pk[bb][1] = pk2(y2, y3);
;             }
;             const auto r0 = __builtin_amdgcn_permlane32_swap(pk[0][0], pk[1][0], false, false);
;             const auto r1 = __builtin_amdgcn_permlane32_swap(pk[0][1], pk[1][1], false, false);
;             u32x4 w; w[0] = r0[0]; w[1] = r1[0]; w[2] = r0[1]; w[3] = r1[1];
;             *(u32x4*)(a.og + oo2 + 32 * m + 16 * bp) = w;
;             __builtin_amdgcn_sched_barrier(0);
;           }
	v_pk_mul_f32 v[30:31], v[136:137], v[40:41]
	v_pk_mul_f32 v[40:41], v[138:139], v[42:43]
	v_lshlrev_b32_e32 v42, 16, v24
	v_and_b32_e32 v43, 0xffff0000, v24
	v_lshlrev_b32_e32 v24, 16, v25
	v_and_b32_e32 v25, 0xffff0000, v25
	v_lshlrev_b32_e32 v44, 16, v23
	v_and_b32_e32 v45, 0xffff0000, v23
	v_lshlrev_b32_e32 v46, 16, v140
	v_and_b32_e32 v47, 0xffff0000, v140
	v_mul_f32_e32 v23, 0xbfb8aa3b, v42
	v_pk_mul_f32 v[26:27], v[26:27], v[42:43]
	v_mul_f32_e32 v42, 0xbfb8aa3b, v43
	v_mul_f32_e32 v43, 0xbfb8aa3b, v24
	v_pk_mul_f32 v[28:29], v[28:29], v[24:25]
	v_mul_f32_e32 v136, 0xbfb8aa3b, v25
	v_mul_f32_e32 v137, 0xbfb8aa3b, v44
	v_pk_mul_f32 v[24:25], v[30:31], v[44:45]
	v_mul_f32_e32 v44, 0xbfb8aa3b, v45
	v_mul_f32_e32 v45, 0xbfb8aa3b, v46
	v_pk_mul_f32 v[30:31], v[40:41], v[46:47]
	v_mul_f32_e32 v40, 0xbfb8aa3b, v47
	v_exp_f32_e32 v23, v23
	v_exp_f32_e32 v41, v42
	v_exp_f32_e32 v42, v43
	v_exp_f32_e32 v43, v136
	v_exp_f32_e32 v46, v137
	v_exp_f32_e32 v44, v44
	v_exp_f32_e32 v45, v45
	v_exp_f32_e32 v40, v40
	v_add_f32_e32 v23, 1.0, v23
	v_add_f32_e32 v41, 1.0, v41
	v_add_f32_e32 v42, 1.0, v42
	v_add_f32_e32 v43, 1.0, v43
	v_add_f32_e32 v46, 1.0, v46
	v_add_f32_e32 v47, 1.0, v44
	v_add_f32_e32 v136, 1.0, v45
	v_add_f32_e32 v137, 1.0, v40
	v_rcp_f32_e32 v40, v23
	v_rcp_f32_e32 v41, v41
	v_rcp_f32_e32 v42, v42
	v_rcp_f32_e32 v43, v43
	v_rcp_f32_e32 v44, v46
	v_rcp_f32_e32 v45, v47
	v_rcp_f32_e32 v46, v136
	v_rcp_f32_e32 v47, v137
	v_pk_mul_f32 v[26:27], v[26:27], v[40:41]
	v_pk_mul_f32 v[28:29], v[28:29], v[42:43]
	v_pk_mul_f32 v[40:41], v[44:45], v[24:25]
	v_pk_mul_f32 v[30:31], v[46:47], v[30:31]
	v_cvt_pk_bf16_f32 v24, v26, v27
	v_cvt_pk_bf16_f32 v25, v28, v29
	v_cvt_pk_bf16_f32 v26, v40, v41
	v_cvt_pk_bf16_f32 v27, v30, v31
	s_nop 0
	v_permlane32_swap_b32_e32 v24, v26
	v_permlane32_swap_b32_e32 v25, v27
	global_store_dwordx4 v[14:15], v[24:27], off offset:32
	s_nop 0
	global_load_dwordx4 v[28:31], v22, s[46:47] offset:128
	global_load_dwordx4 v[40:43], v22, s[46:47] offset:160
	s_waitcnt vmcnt(17)
	v_mov_b32_e32 v24, v164
	v_mov_b32_e32 v25, v165
	v_mov_b32_e32 v26, v166
	v_mov_b32_e32 v27, v167
	v_pk_mul_f32 v[46:47], v[132:133], v[0:1] op_sel_hi:[1,0]
	v_pk_mul_f32 v[44:45], v[134:135], v[0:1] op_sel_hi:[1,0]
	v_pk_mul_f32 v[130:131], v[130:131], v[0:1] op_sel_hi:[1,0]
	v_pk_mul_f32 v[128:129], v[128:129], v[0:1] op_sel_hi:[1,0]
	s_waitcnt vmcnt(2)
	v_mov_b32_e32 v23, v26
	v_mov_b32_e32 v132, v27
	s_nop 0
	v_permlane32_swap_b32_e32 v24, v23
	v_permlane32_swap_b32_e32 v25, v132
	s_waitcnt vmcnt(1)
	v_pk_mul_f32 v[26:27], v[44:45], v[28:29]
	v_pk_mul_f32 v[28:29], v[46:47], v[30:31]
	s_waitcnt vmcnt(0)
	v_pk_mul_f32 v[30:31], v[130:131], v[40:41]
	v_pk_mul_f32 v[40:41], v[128:129], v[42:43]
	v_lshlrev_b32_e32 v42, 16, v24
	v_and_b32_e32 v43, 0xffff0000, v24
	v_lshlrev_b32_e32 v24, 16, v25
	v_and_b32_e32 v25, 0xffff0000, v25
	v_lshlrev_b32_e32 v44, 16, v23
	v_and_b32_e32 v45, 0xffff0000, v23
	v_lshlrev_b32_e32 v46, 16, v132
	v_and_b32_e32 v47, 0xffff0000, v132
	v_mul_f32_e32 v23, 0xbfb8aa3b, v42
	v_pk_mul_f32 v[26:27], v[26:27], v[42:43]
	v_mul_f32_e32 v42, 0xbfb8aa3b, v43
	v_mul_f32_e32 v43, 0xbfb8aa3b, v24
	v_pk_mul_f32 v[28:29], v[28:29], v[24:25]
	v_mul_f32_e32 v128, 0xbfb8aa3b, v25
	v_mul_f32_e32 v129, 0xbfb8aa3b, v44
	v_pk_mul_f32 v[24:25], v[30:31], v[44:45]
	v_mul_f32_e32 v44, 0xbfb8aa3b, v45
	v_mul_f32_e32 v45, 0xbfb8aa3b, v46
	v_pk_mul_f32 v[30:31], v[40:41], v[46:47]
	v_mul_f32_e32 v40, 0xbfb8aa3b, v47
	v_exp_f32_e32 v23, v23
	v_exp_f32_e32 v41, v42
	v_exp_f32_e32 v42, v43
	v_exp_f32_e32 v43, v128
	v_exp_f32_e32 v46, v129
	v_exp_f32_e32 v44, v44
	v_exp_f32_e32 v45, v45
	v_exp_f32_e32 v40, v40
	v_add_f32_e32 v23, 1.0, v23
	v_add_f32_e32 v41, 1.0, v41
	v_add_f32_e32 v42, 1.0, v42
	v_add_f32_e32 v43, 1.0, v43
	v_add_f32_e32 v46, 1.0, v46
	v_add_f32_e32 v47, 1.0, v44
	v_add_f32_e32 v128, 1.0, v45
	v_add_f32_e32 v129, 1.0, v40
	v_rcp_f32_e32 v40, v23
	v_rcp_f32_e32 v41, v41
	v_rcp_f32_e32 v42, v42
	v_rcp_f32_e32 v43, v43
	v_rcp_f32_e32 v44, v46
	v_rcp_f32_e32 v45, v47
	v_rcp_f32_e32 v46, v128
	v_rcp_f32_e32 v47, v129
	v_pk_mul_f32 v[26:27], v[26:27], v[40:41]
	v_pk_mul_f32 v[28:29], v[28:29], v[42:43]
	v_pk_mul_f32 v[40:41], v[44:45], v[24:25]
	v_pk_mul_f32 v[30:31], v[46:47], v[30:31]
	v_cvt_pk_bf16_f32 v24, v26, v27
	v_cvt_pk_bf16_f32 v25, v28, v29
	v_cvt_pk_bf16_f32 v26, v40, v41
	v_cvt_pk_bf16_f32 v27, v30, v31
	s_nop 0
	v_permlane32_swap_b32_e32 v24, v26
	v_permlane32_swap_b32_e32 v25, v27
	global_store_dwordx4 v[14:15], v[24:27], off offset:64
	s_nop 0
	global_load_dwordx4 v[28:31], v22, s[46:47] offset:192
	global_load_dwordx4 v[40:43], v22, s[46:47] offset:224
	s_waitcnt vmcnt(17)
	v_mov_b32_e32 v24, v168
	v_mov_b32_e32 v25, v169
	v_mov_b32_e32 v26, v170
	v_mov_b32_e32 v27, v171
	v_pk_mul_f32 v[44:45], v[120:121], v[0:1] op_sel_hi:[1,0]
	v_pk_mul_f32 v[120:121], v[124:125], v[0:1] op_sel_hi:[1,0]
	v_pk_mul_f32 v[46:47], v[122:123], v[0:1] op_sel_hi:[1,0]
	v_pk_mul_f32 v[122:123], v[126:127], v[0:1] op_sel_hi:[1,0]
	s_waitcnt vmcnt(2)
	v_mov_b32_e32 v23, v26
	v_mov_b32_e32 v124, v27
	s_nop 0
	v_permlane32_swap_b32_e32 v24, v23
	v_permlane32_swap_b32_e32 v25, v124
	s_waitcnt vmcnt(1)
	v_pk_mul_f32 v[26:27], v[44:45], v[28:29]
	v_pk_mul_f32 v[28:29], v[46:47], v[30:31]
	s_waitcnt vmcnt(0)
; DI u32 pk2(float a, float b) { f2_t v = {a, b}; bf2_t r = __builtin_convertvector(v, bf2_t); return __builtin_bit_cast(u32, r); }
; DI float bflo(u32 u) { return __uint_as_float(u << 16); }
; DI float bfhi(u32 u) { return __uint_as_float(u & 0xffff0000u); }
; template <bool DIFF>
; DI void attn_phase(const AttnArgs& a, char* lds) {
;     ...
; #pragma unroll
;         for (int m = 0; m < NM; ++m)
; #pragma unroll
;           for (int bp = 0; bp < 2; ++bp) {
;             u32x2 pk[2];
;             const u32x4 gl = *(const u32x4*)(a.gate + go2 + 32 * m + 16 * bp);
;             const auto q0 = __builtin_amdgcn_permlane32_swap(gl[0], gl[2], false, false);
;             const auto q1 = __builtin_amdgcn_permlane32_swap(gl[1], gl[3], false, false);
;             u32x2 gsel[2]; gsel[0][0] = q0[0]; gsel[0][1] = q1[0]; gsel[1][0] = q0[1]; gsel[1][1] = q1[1];
; #pragma unroll
;             for (int bb = 0; bb < 2; ++bb) {
;               const int b = 2 * bp + bb;
;               const int dv = 32 * m + 8 * b;
;               const u32x2 gu = gsel[bb];
;               const float4 sg = *(const float4*)(a.subln + dv + 4 * g);
;               const float g0 = bflo(gu[0]), g1 = bfhi(gu[0]), g2 = bflo(gu[1]), g3 = bfhi(gu[1]);
;               const float y0 = o[m][4 * b] * rn * sg.x * g0 * __builtin_amdgcn_rcpf(1.f + __expf(-g0));
;               const float y1 = o[m][4 * b + 1] * rn * sg.y * g1 * __builtin_amdgcn_rcpf(1.f + __expf(-g1));
;               const float y2 = o[m][4 * b + 2] * rn * sg.z * g2 * __builtin_amdgcn_rcpf(1.f + __expf(-g2));
;               const float y3 = o[m][4 * b + 3] * rn * sg.w * g3 * __builtin_amdgcn_rcpf(1.f + __expf(-g3));
;               pk[bb][0] = pk2(y0, y1); pk[bb][1] = pk2(y2, y3);
;             }
;             const auto r0 = __builtin_amdgcn_permlane32_swap(pk[0][0], pk[1][0], false, false);
;             const auto r1 = __builtin_amdgcn_permlane32_swap(pk[0][1], pk[1][1], false, false);
;             u32x4 w; w[0] = r0[0]; w[1] = r1[0]; w[2] = r0[1]; w[3] = r1[1];
;             *(u32x4*)(a.og + oo2 + 32 * m + 16 * bp) = w;
;             __builtin_amdgcn_sched_barrier(0);
;           }
	v_pk_mul_f32 v[30:31], v[120:121], v[40:41]
	v_pk_mul_f32 v[40:41], v[122:123], v[42:43]
	v_lshlrev_b32_e32 v42, 16, v24
	v_and_b32_e32 v43, 0xffff0000, v24
	v_lshlrev_b32_e32 v24, 16, v25
	v_and_b32_e32 v25, 0xffff0000, v25
	v_lshlrev_b32_e32 v44, 16, v23
	v_and_b32_e32 v45, 0xffff0000, v23
	v_lshlrev_b32_e32 v46, 16, v124
	v_and_b32_e32 v47, 0xffff0000, v124
	v_mul_f32_e32 v23, 0xbfb8aa3b, v42
	v_pk_mul_f32 v[26:27], v[26:27], v[42:43]
	v_mul_f32_e32 v42, 0xbfb8aa3b, v43
	v_mul_f32_e32 v43, 0xbfb8aa3b, v24
	v_pk_mul_f32 v[28:29], v[28:29], v[24:25]
	v_mul_f32_e32 v120, 0xbfb8aa3b, v25
	v_mul_f32_e32 v121, 0xbfb8aa3b, v44
	v_pk_mul_f32 v[24:25], v[30:31], v[44:45]
	v_mul_f32_e32 v44, 0xbfb8aa3b, v45
	v_mul_f32_e32 v45, 0xbfb8aa3b, v46
	v_pk_mul_f32 v[30:31], v[40:41], v[46:47]
	v_mul_f32_e32 v40, 0xbfb8aa3b, v47
	v_exp_f32_e32 v23, v23
	v_exp_f32_e32 v41, v42
	v_exp_f32_e32 v42, v43
	v_exp_f32_e32 v43, v120
	v_exp_f32_e32 v46, v121
	v_exp_f32_e32 v44, v44
	v_exp_f32_e32 v45, v45
	v_exp_f32_e32 v40, v40
	v_add_f32_e32 v23, 1.0, v23
	v_add_f32_e32 v41, 1.0, v41
	v_add_f32_e32 v42, 1.0, v42
	v_add_f32_e32 v43, 1.0, v43
	v_add_f32_e32 v46, 1.0, v46
	v_add_f32_e32 v47, 1.0, v44
	v_add_f32_e32 v120, 1.0, v45
	v_add_f32_e32 v121, 1.0, v40
	v_rcp_f32_e32 v40, v23
	v_rcp_f32_e32 v41, v41
	v_rcp_f32_e32 v42, v42
	v_rcp_f32_e32 v43, v43
	v_rcp_f32_e32 v44, v46
	v_rcp_f32_e32 v45, v47
	v_rcp_f32_e32 v46, v120
	v_rcp_f32_e32 v47, v121
	v_pk_mul_f32 v[26:27], v[26:27], v[40:41]
	v_pk_mul_f32 v[28:29], v[28:29], v[42:43]
	v_pk_mul_f32 v[40:41], v[44:45], v[24:25]
	v_pk_mul_f32 v[30:31], v[46:47], v[30:31]
	v_cvt_pk_bf16_f32 v24, v26, v27
	v_cvt_pk_bf16_f32 v25, v28, v29
	v_cvt_pk_bf16_f32 v26, v40, v41
	v_cvt_pk_bf16_f32 v27, v30, v31
	s_nop 0
	v_permlane32_swap_b32_e32 v24, v26
	v_permlane32_swap_b32_e32 v25, v27
	global_store_dwordx4 v[14:15], v[24:27], off offset:96
	s_nop 0
	global_load_dwordx4 v[28:31], v22, s[46:47] offset:256
	global_load_dwordx4 v[40:43], v22, s[46:47] offset:288
	s_waitcnt vmcnt(17)
	v_mov_b32_e32 v24, v172
	v_mov_b32_e32 v25, v173
	v_mov_b32_e32 v26, v174
	v_mov_b32_e32 v27, v175
	v_pk_mul_f32 v[46:47], v[116:117], v[0:1] op_sel_hi:[1,0]
	v_pk_mul_f32 v[44:45], v[118:119], v[0:1] op_sel_hi:[1,0]
	v_pk_mul_f32 v[114:115], v[114:115], v[0:1] op_sel_hi:[1,0]
	v_pk_mul_f32 v[112:113], v[112:113], v[0:1] op_sel_hi:[1,0]
	s_waitcnt vmcnt(2)
	v_mov_b32_e32 v23, v26
	v_mov_b32_e32 v116, v27
	s_nop 0
	v_permlane32_swap_b32_e32 v24, v23
	v_permlane32_swap_b32_e32 v25, v116
	s_waitcnt vmcnt(1)
	v_pk_mul_f32 v[26:27], v[44:45], v[28:29]
	v_pk_mul_f32 v[28:29], v[46:47], v[30:31]
	s_waitcnt vmcnt(0)
	v_pk_mul_f32 v[30:31], v[114:115], v[40:41]
	v_pk_mul_f32 v[40:41], v[112:113], v[42:43]
	v_lshlrev_b32_e32 v42, 16, v24
	v_and_b32_e32 v43, 0xffff0000, v24
	v_lshlrev_b32_e32 v24, 16, v25
	v_and_b32_e32 v25, 0xffff0000, v25
	v_lshlrev_b32_e32 v44, 16, v23
	v_and_b32_e32 v45, 0xffff0000, v23
	v_lshlrev_b32_e32 v46, 16, v116
	v_and_b32_e32 v47, 0xffff0000, v116
	v_mul_f32_e32 v23, 0xbfb8aa3b, v42
	v_pk_mul_f32 v[26:27], v[26:27], v[42:43]
	v_mul_f32_e32 v42, 0xbfb8aa3b, v43
	v_mul_f32_e32 v43, 0xbfb8aa3b, v24
	v_pk_mul_f32 v[28:29], v[28:29], v[24:25]
	v_mul_f32_e32 v112, 0xbfb8aa3b, v25
	v_mul_f32_e32 v113, 0xbfb8aa3b, v44
	v_pk_mul_f32 v[24:25], v[30:31], v[44:45]
	v_mul_f32_e32 v44, 0xbfb8aa3b, v45
	v_mul_f32_e32 v45, 0xbfb8aa3b, v46
	v_pk_mul_f32 v[30:31], v[40:41], v[46:47]
	v_mul_f32_e32 v40, 0xbfb8aa3b, v47
	v_exp_f32_e32 v23, v23
	v_exp_f32_e32 v41, v42
	v_exp_f32_e32 v42, v43
	v_exp_f32_e32 v43, v112
	v_exp_f32_e32 v46, v113
	v_exp_f32_e32 v44, v44
	v_exp_f32_e32 v45, v45
	v_exp_f32_e32 v40, v40
	v_add_f32_e32 v23, 1.0, v23
	v_add_f32_e32 v41, 1.0, v41
	v_add_f32_e32 v42, 1.0, v42
	v_add_f32_e32 v43, 1.0, v43
	v_add_f32_e32 v46, 1.0, v46
	v_add_f32_e32 v47, 1.0, v44
	v_add_f32_e32 v112, 1.0, v45
	v_add_f32_e32 v113, 1.0, v40
	v_rcp_f32_e32 v40, v23
	v_rcp_f32_e32 v41, v41
	v_rcp_f32_e32 v42, v42
	v_rcp_f32_e32 v43, v43
	v_rcp_f32_e32 v44, v46
	v_rcp_f32_e32 v45, v47
	v_rcp_f32_e32 v46, v112
	v_rcp_f32_e32 v47, v113
	v_pk_mul_f32 v[26:27], v[26:27], v[40:41]
	v_pk_mul_f32 v[28:29], v[28:29], v[42:43]
	v_pk_mul_f32 v[40:41], v[44:45], v[24:25]
	v_pk_mul_f32 v[30:31], v[46:47], v[30:31]
	v_cvt_pk_bf16_f32 v24, v26, v27
	v_cvt_pk_bf16_f32 v25, v28, v29
	v_cvt_pk_bf16_f32 v26, v40, v41
	v_cvt_pk_bf16_f32 v27, v30, v31
	s_nop 0
	v_permlane32_swap_b32_e32 v24, v26
	v_permlane32_swap_b32_e32 v25, v27
	global_store_dwordx4 v[14:15], v[24:27], off offset:128
	s_nop 0
	global_load_dwordx4 v[28:31], v22, s[46:47] offset:320
	global_load_dwordx4 v[40:43], v22, s[46:47] offset:352
	s_waitcnt vmcnt(17)
	v_mov_b32_e32 v24, v176
	v_mov_b32_e32 v25, v177
	v_mov_b32_e32 v26, v178
	v_mov_b32_e32 v27, v179
	v_pk_mul_f32 v[44:45], v[104:105], v[0:1] op_sel_hi:[1,0]
	v_pk_mul_f32 v[104:105], v[108:109], v[0:1] op_sel_hi:[1,0]
	v_pk_mul_f32 v[46:47], v[106:107], v[0:1] op_sel_hi:[1,0]
	v_pk_mul_f32 v[106:107], v[110:111], v[0:1] op_sel_hi:[1,0]
	s_waitcnt vmcnt(2)
	v_mov_b32_e32 v23, v26
	v_mov_b32_e32 v108, v27
	s_nop 0
	v_permlane32_swap_b32_e32 v24, v23
	v_permlane32_swap_b32_e32 v25, v108
	s_waitcnt vmcnt(1)
	v_pk_mul_f32 v[26:27], v[44:45], v[28:29]
	v_pk_mul_f32 v[28:29], v[46:47], v[30:31]
	s_waitcnt vmcnt(0)
; DI u32 pk2(float a, float b) { f2_t v = {a, b}; bf2_t r = __builtin_convertvector(v, bf2_t); return __builtin_bit_cast(u32, r); }
; DI float bflo(u32 u) { return __uint_as_float(u << 16); }
; DI float bfhi(u32 u) { return __uint_as_float(u & 0xffff0000u); }
; template <bool DIFF>
; DI void attn_phase(const AttnArgs& a, char* lds) {
;     ...
; #pragma unroll
;         for (int m = 0; m < NM; ++m)
; #pragma unroll
;           for (int bp = 0; bp < 2; ++bp) {
;             u32x2 pk[2];
;             const u32x4 gl = *(const u32x4*)(a.gate + go2 + 32 * m + 16 * bp);
;             const auto q0 = __builtin_amdgcn_permlane32_swap(gl[0], gl[2], false, false);
;             const auto q1 = __builtin_amdgcn_permlane32_swap(gl[1], gl[3], false, false);
;             u32x2 gsel[2]; gsel[0][0] = q0[0]; gsel[0][1] = q1[0]; gsel[1][0] = q0[1]; gsel[1][1] = q1[1];
; #pragma unroll
;             for (int bb = 0; bb < 2; ++bb) {
;               const int b = 2 * bp + bb;
;               const int dv = 32 * m + 8 * b;
;               const u32x2 gu = gsel[bb];
;               const float4 sg = *(const float4*)(a.subln + dv + 4 * g);
;               const float g0 = bflo(gu[0]), g1 = bfhi(gu[0]), g2 = bflo(gu[1]), g3 = bfhi(gu[1]);
;               const float y0 = o[m][4 * b] * rn * sg.x * g0 * __builtin_amdgcn_rcpf(1.f + __expf(-g0));
;               const float y1 = o[m][4 * b + 1] * rn * sg.y * g1 * __builtin_amdgcn_rcpf(1.f + __expf(-g1));
;               const float y2 = o[m][4 * b + 2] * rn * sg.z * g2 * __builtin_amdgcn_rcpf(1.f + __expf(-g2));
;               const float y3 = o[m][4 * b + 3] * rn * sg.w * g3 * __builtin_amdgcn_rcpf(1.f + __expf(-g3));
;               pk[bb][0] = pk2(y0, y1); pk[bb][1] = pk2(y2, y3);
;             }
;             const auto r0 = __builtin_amdgcn_permlane32_swap(pk[0][0], pk[1][0], false, false);
;             const auto r1 = __builtin_amdgcn_permlane32_swap(pk[0][1], pk[1][1], false, false);
;             u32x4 w; w[0] = r0[0]; w[1] = r1[0]; w[2] = r0[1]; w[3] = r1[1];
;             *(u32x4*)(a.og + oo2 + 32 * m + 16 * bp) = w;
;             __builtin_amdgcn_sched_barrier(0);
;           }
	v_pk_mul_f32 v[30:31], v[104:105], v[40:41]
	v_pk_mul_f32 v[40:41], v[106:107], v[42:43]
	v_lshlrev_b32_e32 v42, 16, v24
	v_and_b32_e32 v43, 0xffff0000, v24
	v_lshlrev_b32_e32 v24, 16, v25
	v_and_b32_e32 v25, 0xffff0000, v25
	v_lshlrev_b32_e32 v44, 16, v23
	v_and_b32_e32 v45, 0xffff0000, v23
	v_lshlrev_b32_e32 v46, 16, v108
	v_and_b32_e32 v47, 0xffff0000, v108
	v_mul_f32_e32 v23, 0xbfb8aa3b, v42
	v_pk_mul_f32 v[26:27], v[26:27], v[42:43]
	v_mul_f32_e32 v42, 0xbfb8aa3b, v43
	v_mul_f32_e32 v43, 0xbfb8aa3b, v24
	v_pk_mul_f32 v[28:29], v[28:29], v[24:25]
	v_mul_f32_e32 v104, 0xbfb8aa3b, v25
	v_mul_f32_e32 v105, 0xbfb8aa3b, v44
	v_pk_mul_f32 v[24:25], v[30:31], v[44:45]
	v_mul_f32_e32 v44, 0xbfb8aa3b, v45
	v_mul_f32_e32 v45, 0xbfb8aa3b, v46
	v_pk_mul_f32 v[30:31], v[40:41], v[46:47]
	v_mul_f32_e32 v40, 0xbfb8aa3b, v47
	v_exp_f32_e32 v23, v23
	v_exp_f32_e32 v41, v42
	v_exp_f32_e32 v42, v43
	v_exp_f32_e32 v43, v104
	v_exp_f32_e32 v46, v105
	v_exp_f32_e32 v44, v44
	v_exp_f32_e32 v45, v45
	v_exp_f32_e32 v40, v40
	v_add_f32_e32 v23, 1.0, v23
	v_add_f32_e32 v41, 1.0, v41
	v_add_f32_e32 v42, 1.0, v42
	v_add_f32_e32 v43, 1.0, v43
	v_add_f32_e32 v46, 1.0, v46
	v_add_f32_e32 v47, 1.0, v44
	v_add_f32_e32 v104, 1.0, v45
	v_add_f32_e32 v105, 1.0, v40
	v_rcp_f32_e32 v40, v23
	v_rcp_f32_e32 v41, v41
	v_rcp_f32_e32 v42, v42
	v_rcp_f32_e32 v43, v43
	v_rcp_f32_e32 v44, v46
	v_rcp_f32_e32 v45, v47
	v_rcp_f32_e32 v46, v104
	v_rcp_f32_e32 v47, v105
	v_pk_mul_f32 v[26:27], v[26:27], v[40:41]
	v_pk_mul_f32 v[28:29], v[28:29], v[42:43]
	v_pk_mul_f32 v[40:41], v[44:45], v[24:25]
	v_pk_mul_f32 v[30:31], v[46:47], v[30:31]
	v_cvt_pk_bf16_f32 v24, v26, v27
	v_cvt_pk_bf16_f32 v25, v28, v29
	v_cvt_pk_bf16_f32 v26, v40, v41
	v_cvt_pk_bf16_f32 v27, v30, v31
	s_nop 0
	v_permlane32_swap_b32_e32 v24, v26
	v_permlane32_swap_b32_e32 v25, v27
	global_store_dwordx4 v[14:15], v[24:27], off offset:160
	s_nop 0
	global_load_dwordx4 v[28:31], v22, s[46:47] offset:384
	global_load_dwordx4 v[40:43], v22, s[46:47] offset:416
	s_waitcnt vmcnt(17)
	v_mov_b32_e32 v24, v180
	v_mov_b32_e32 v25, v181
	v_mov_b32_e32 v26, v182
	v_mov_b32_e32 v27, v183
	v_pk_mul_f32 v[46:47], v[100:101], v[0:1] op_sel_hi:[1,0]
	v_pk_mul_f32 v[44:45], v[102:103], v[0:1] op_sel_hi:[1,0]
	v_pk_mul_f32 v[98:99], v[98:99], v[0:1] op_sel_hi:[1,0]
	v_pk_mul_f32 v[96:97], v[96:97], v[0:1] op_sel_hi:[1,0]
	s_waitcnt vmcnt(2)
	v_mov_b32_e32 v23, v26
	v_mov_b32_e32 v100, v27
	s_nop 0
	v_permlane32_swap_b32_e32 v24, v23
	v_permlane32_swap_b32_e32 v25, v100
	s_waitcnt vmcnt(1)
	v_pk_mul_f32 v[26:27], v[44:45], v[28:29]
	v_pk_mul_f32 v[28:29], v[46:47], v[30:31]
	s_waitcnt vmcnt(0)
	v_pk_mul_f32 v[30:31], v[98:99], v[40:41]
	v_pk_mul_f32 v[40:41], v[96:97], v[42:43]
	v_lshlrev_b32_e32 v42, 16, v24
	v_and_b32_e32 v43, 0xffff0000, v24
	v_lshlrev_b32_e32 v24, 16, v25
	v_and_b32_e32 v25, 0xffff0000, v25
	v_lshlrev_b32_e32 v44, 16, v23
	v_and_b32_e32 v45, 0xffff0000, v23
	v_lshlrev_b32_e32 v46, 16, v100
	v_and_b32_e32 v47, 0xffff0000, v100
	v_mul_f32_e32 v23, 0xbfb8aa3b, v42
	v_pk_mul_f32 v[26:27], v[26:27], v[42:43]
	v_mul_f32_e32 v42, 0xbfb8aa3b, v43
	v_mul_f32_e32 v43, 0xbfb8aa3b, v24
	v_pk_mul_f32 v[28:29], v[28:29], v[24:25]
	v_mul_f32_e32 v96, 0xbfb8aa3b, v25
	v_mul_f32_e32 v97, 0xbfb8aa3b, v44
	v_pk_mul_f32 v[24:25], v[30:31], v[44:45]
	v_mul_f32_e32 v44, 0xbfb8aa3b, v45
	v_mul_f32_e32 v45, 0xbfb8aa3b, v46
	v_pk_mul_f32 v[30:31], v[40:41], v[46:47]
	v_mul_f32_e32 v40, 0xbfb8aa3b, v47
	v_exp_f32_e32 v23, v23
	v_exp_f32_e32 v41, v42
	v_exp_f32_e32 v42, v43
	v_exp_f32_e32 v43, v96
	v_exp_f32_e32 v46, v97
	v_exp_f32_e32 v44, v44
	v_exp_f32_e32 v45, v45
	v_exp_f32_e32 v40, v40
	v_add_f32_e32 v23, 1.0, v23
	v_add_f32_e32 v41, 1.0, v41
	v_add_f32_e32 v42, 1.0, v42
	v_add_f32_e32 v43, 1.0, v43
	v_add_f32_e32 v46, 1.0, v46
	v_add_f32_e32 v47, 1.0, v44
	v_add_f32_e32 v96, 1.0, v45
	v_add_f32_e32 v97, 1.0, v40
	v_rcp_f32_e32 v40, v23
	v_rcp_f32_e32 v41, v41
	v_rcp_f32_e32 v42, v42
	v_rcp_f32_e32 v43, v43
	v_rcp_f32_e32 v44, v46
	v_rcp_f32_e32 v45, v47
	v_rcp_f32_e32 v46, v96
	v_rcp_f32_e32 v47, v97
	v_pk_mul_f32 v[26:27], v[26:27], v[40:41]
	v_pk_mul_f32 v[28:29], v[28:29], v[42:43]
	v_pk_mul_f32 v[40:41], v[44:45], v[24:25]
	v_pk_mul_f32 v[30:31], v[46:47], v[30:31]
	v_cvt_pk_bf16_f32 v24, v26, v27
	v_cvt_pk_bf16_f32 v25, v28, v29
	v_cvt_pk_bf16_f32 v26, v40, v41
	v_cvt_pk_bf16_f32 v27, v30, v31
	s_nop 0
	v_permlane32_swap_b32_e32 v24, v26
	v_permlane32_swap_b32_e32 v25, v27
	global_store_dwordx4 v[14:15], v[24:27], off offset:192
	s_nop 0
	global_load_dwordx4 v[28:31], v22, s[46:47] offset:448
	global_load_dwordx4 v[40:43], v22, s[46:47] offset:480
	s_waitcnt vmcnt(17)
	v_mov_b32_e32 v24, v184
	v_mov_b32_e32 v25, v185
	v_mov_b32_e32 v26, v186
	v_mov_b32_e32 v27, v187
	v_pk_mul_f32 v[44:45], v[88:89], v[0:1] op_sel_hi:[1,0]
	v_pk_mul_f32 v[88:89], v[92:93], v[0:1] op_sel_hi:[1,0]
	v_pk_mul_f32 v[46:47], v[90:91], v[0:1] op_sel_hi:[1,0]
	v_pk_mul_f32 v[90:91], v[94:95], v[0:1] op_sel_hi:[1,0]
	s_waitcnt vmcnt(2)
	v_mov_b32_e32 v23, v26
	v_mov_b32_e32 v92, v27
	s_nop 0
	v_permlane32_swap_b32_e32 v24, v23
	v_permlane32_swap_b32_e32 v25, v92
	s_waitcnt vmcnt(1)
	v_pk_mul_f32 v[26:27], v[44:45], v[28:29]
	v_pk_mul_f32 v[28:29], v[46:47], v[30:31]
	s_waitcnt vmcnt(0)
; DI u32 pk2(float a, float b) { f2_t v = {a, b}; bf2_t r = __builtin_convertvector(v, bf2_t); return __builtin_bit_cast(u32, r); }
; DI float bflo(u32 u) { return __uint_as_float(u << 16); }
; DI float bfhi(u32 u) { return __uint_as_float(u & 0xffff0000u); }
; template <bool DIFF>
; DI void attn_phase(const AttnArgs& a, char* lds) {
;     ...
; #pragma unroll
;         for (int m = 0; m < NM; ++m)
; #pragma unroll
;           for (int bp = 0; bp < 2; ++bp) {
;             u32x2 pk[2];
;             const u32x4 gl = *(const u32x4*)(a.gate + go2 + 32 * m + 16 * bp);
;             const auto q0 = __builtin_amdgcn_permlane32_swap(gl[0], gl[2], false, false);
;             const auto q1 = __builtin_amdgcn_permlane32_swap(gl[1], gl[3], false, false);
;             u32x2 gsel[2]; gsel[0][0] = q0[0]; gsel[0][1] = q1[0]; gsel[1][0] = q0[1]; gsel[1][1] = q1[1];
; #pragma unroll
;             for (int bb = 0; bb < 2; ++bb) {
;               const int b = 2 * bp + bb;
;               const int dv = 32 * m + 8 * b;
;               const u32x2 gu = gsel[bb];
;               const float4 sg = *(const float4*)(a.subln + dv + 4 * g);
;               const float g0 = bflo(gu[0]), g1 = bfhi(gu[0]), g2 = bflo(gu[1]), g3 = bfhi(gu[1]);
;               const float y0 = o[m][4 * b] * rn * sg.x * g0 * __builtin_amdgcn_rcpf(1.f + __expf(-g0));
;               const float y1 = o[m][4 * b + 1] * rn * sg.y * g1 * __builtin_amdgcn_rcpf(1.f + __expf(-g1));
;               const float y2 = o[m][4 * b + 2] * rn * sg.z * g2 * __builtin_amdgcn_rcpf(1.f + __expf(-g2));
;               const float y3 = o[m][4 * b + 3] * rn * sg.w * g3 * __builtin_amdgcn_rcpf(1.f + __expf(-g3));
;               pk[bb][0] = pk2(y0, y1); pk[bb][1] = pk2(y2, y3);
;             }
;             const auto r0 = __builtin_amdgcn_permlane32_swap(pk[0][0], pk[1][0], false, false);
;             const auto r1 = __builtin_amdgcn_permlane32_swap(pk[0][1], pk[1][1], false, false);
;             u32x4 w; w[0] = r0[0]; w[1] = r1[0]; w[2] = r0[1]; w[3] = r1[1];
;             *(u32x4*)(a.og + oo2 + 32 * m + 16 * bp) = w;
;             __builtin_amdgcn_sched_barrier(0);
;           }
	v_pk_mul_f32 v[30:31], v[88:89], v[40:41]
	v_pk_mul_f32 v[40:41], v[90:91], v[42:43]
	v_lshlrev_b32_e32 v42, 16, v24
	v_and_b32_e32 v43, 0xffff0000, v24
	v_lshlrev_b32_e32 v24, 16, v25
	v_and_b32_e32 v25, 0xffff0000, v25
	v_lshlrev_b32_e32 v44, 16, v23
	v_and_b32_e32 v45, 0xffff0000, v23
	v_lshlrev_b32_e32 v46, 16, v92
	v_and_b32_e32 v47, 0xffff0000, v92
	v_mul_f32_e32 v23, 0xbfb8aa3b, v42
	v_pk_mul_f32 v[26:27], v[26:27], v[42:43]
	v_mul_f32_e32 v42, 0xbfb8aa3b, v43
	v_mul_f32_e32 v43, 0xbfb8aa3b, v24
	v_pk_mul_f32 v[28:29], v[28:29], v[24:25]
	v_mul_f32_e32 v88, 0xbfb8aa3b, v25
	v_mul_f32_e32 v89, 0xbfb8aa3b, v44
	v_pk_mul_f32 v[24:25], v[30:31], v[44:45]
	v_mul_f32_e32 v44, 0xbfb8aa3b, v45
	v_mul_f32_e32 v45, 0xbfb8aa3b, v46
	v_pk_mul_f32 v[30:31], v[40:41], v[46:47]
	v_mul_f32_e32 v40, 0xbfb8aa3b, v47
	v_exp_f32_e32 v23, v23
	v_exp_f32_e32 v41, v42
	v_exp_f32_e32 v42, v43
	v_exp_f32_e32 v43, v88
	v_exp_f32_e32 v46, v89
	v_exp_f32_e32 v44, v44
	v_exp_f32_e32 v45, v45
	v_exp_f32_e32 v40, v40
	v_add_f32_e32 v23, 1.0, v23
	v_add_f32_e32 v41, 1.0, v41
	v_add_f32_e32 v42, 1.0, v42
	v_add_f32_e32 v43, 1.0, v43
	v_add_f32_e32 v46, 1.0, v46
	v_add_f32_e32 v47, 1.0, v44
	v_add_f32_e32 v88, 1.0, v45
	v_add_f32_e32 v89, 1.0, v40
	v_rcp_f32_e32 v40, v23
	v_rcp_f32_e32 v41, v41
	v_rcp_f32_e32 v42, v42
	v_rcp_f32_e32 v43, v43
	v_rcp_f32_e32 v44, v46
	v_rcp_f32_e32 v45, v47
	v_rcp_f32_e32 v46, v88
	v_rcp_f32_e32 v47, v89
	v_pk_mul_f32 v[26:27], v[26:27], v[40:41]
	v_pk_mul_f32 v[28:29], v[28:29], v[42:43]
	v_pk_mul_f32 v[40:41], v[44:45], v[24:25]
	v_pk_mul_f32 v[30:31], v[46:47], v[30:31]
	v_cvt_pk_bf16_f32 v24, v26, v27
	v_cvt_pk_bf16_f32 v25, v28, v29
	v_cvt_pk_bf16_f32 v26, v40, v41
	v_cvt_pk_bf16_f32 v27, v30, v31
	s_nop 0
	v_permlane32_swap_b32_e32 v24, v26
	v_permlane32_swap_b32_e32 v25, v27
	global_store_dwordx4 v[14:15], v[24:27], off offset:224
	s_nop 0
	global_load_dwordx4 v[28:31], v22, s[46:47] offset:512
	global_load_dwordx4 v[40:43], v22, s[46:47] offset:544
	s_waitcnt vmcnt(17)
	v_mov_b32_e32 v24, v188
	v_mov_b32_e32 v25, v189
	v_mov_b32_e32 v26, v190
	v_mov_b32_e32 v27, v191
	v_pk_mul_f32 v[46:47], v[84:85], v[0:1] op_sel_hi:[1,0]
	v_pk_mul_f32 v[44:45], v[86:87], v[0:1] op_sel_hi:[1,0]
	v_pk_mul_f32 v[82:83], v[82:83], v[0:1] op_sel_hi:[1,0]
	v_pk_mul_f32 v[80:81], v[80:81], v[0:1] op_sel_hi:[1,0]
	s_waitcnt vmcnt(2)
	v_mov_b32_e32 v23, v26
	v_mov_b32_e32 v84, v27
	s_nop 0
	v_permlane32_swap_b32_e32 v24, v23
	v_permlane32_swap_b32_e32 v25, v84
	s_waitcnt vmcnt(1)
	v_pk_mul_f32 v[26:27], v[44:45], v[28:29]
	v_pk_mul_f32 v[28:29], v[46:47], v[30:31]
	s_waitcnt vmcnt(0)
	v_pk_mul_f32 v[30:31], v[82:83], v[40:41]
	v_pk_mul_f32 v[40:41], v[80:81], v[42:43]
	v_lshlrev_b32_e32 v42, 16, v24
	v_and_b32_e32 v43, 0xffff0000, v24
	v_lshlrev_b32_e32 v24, 16, v25
	v_and_b32_e32 v25, 0xffff0000, v25
	v_lshlrev_b32_e32 v44, 16, v23
	v_and_b32_e32 v45, 0xffff0000, v23
	v_lshlrev_b32_e32 v46, 16, v84
	v_and_b32_e32 v47, 0xffff0000, v84
	v_mul_f32_e32 v23, 0xbfb8aa3b, v42
	v_pk_mul_f32 v[26:27], v[26:27], v[42:43]
	v_mul_f32_e32 v42, 0xbfb8aa3b, v43
	v_mul_f32_e32 v43, 0xbfb8aa3b, v24
	v_pk_mul_f32 v[28:29], v[28:29], v[24:25]
	v_mul_f32_e32 v80, 0xbfb8aa3b, v25
	v_mul_f32_e32 v81, 0xbfb8aa3b, v44
	v_pk_mul_f32 v[24:25], v[30:31], v[44:45]
	v_mul_f32_e32 v44, 0xbfb8aa3b, v45
	v_mul_f32_e32 v45, 0xbfb8aa3b, v46
	v_pk_mul_f32 v[30:31], v[40:41], v[46:47]
	v_mul_f32_e32 v40, 0xbfb8aa3b, v47
	v_exp_f32_e32 v23, v23
	v_exp_f32_e32 v41, v42
	v_exp_f32_e32 v42, v43
	v_exp_f32_e32 v43, v80
	v_exp_f32_e32 v46, v81
	v_exp_f32_e32 v44, v44
	v_exp_f32_e32 v45, v45
	v_exp_f32_e32 v40, v40
	v_add_f32_e32 v23, 1.0, v23
	v_add_f32_e32 v41, 1.0, v41
	v_add_f32_e32 v42, 1.0, v42
	v_add_f32_e32 v43, 1.0, v43
	v_add_f32_e32 v46, 1.0, v46
	v_add_f32_e32 v47, 1.0, v44
	v_add_f32_e32 v80, 1.0, v45
	v_add_f32_e32 v81, 1.0, v40
	v_rcp_f32_e32 v40, v23
	v_rcp_f32_e32 v41, v41
	v_rcp_f32_e32 v42, v42
	v_rcp_f32_e32 v43, v43
	v_rcp_f32_e32 v44, v46
	v_rcp_f32_e32 v45, v47
	v_rcp_f32_e32 v46, v80
	v_rcp_f32_e32 v47, v81
	v_pk_mul_f32 v[26:27], v[26:27], v[40:41]
	v_pk_mul_f32 v[28:29], v[28:29], v[42:43]
	v_pk_mul_f32 v[40:41], v[44:45], v[24:25]
	v_pk_mul_f32 v[30:31], v[46:47], v[30:31]
	v_cvt_pk_bf16_f32 v24, v26, v27
	v_cvt_pk_bf16_f32 v25, v28, v29
	v_cvt_pk_bf16_f32 v26, v40, v41
	v_cvt_pk_bf16_f32 v27, v30, v31
	s_nop 0
	v_permlane32_swap_b32_e32 v24, v26
	v_permlane32_swap_b32_e32 v25, v27
	global_store_dwordx4 v[14:15], v[24:27], off offset:256
	s_nop 0
	global_load_dwordx4 v[28:31], v22, s[46:47] offset:576
	global_load_dwordx4 v[40:43], v22, s[46:47] offset:608
	s_waitcnt vmcnt(17)
	v_mov_b32_e32 v24, v192
	v_mov_b32_e32 v25, v193
	v_mov_b32_e32 v26, v194
	v_mov_b32_e32 v27, v195
	v_pk_mul_f32 v[44:45], v[72:73], v[0:1] op_sel_hi:[1,0]
	v_pk_mul_f32 v[72:73], v[76:77], v[0:1] op_sel_hi:[1,0]
	v_pk_mul_f32 v[46:47], v[74:75], v[0:1] op_sel_hi:[1,0]
	v_pk_mul_f32 v[74:75], v[78:79], v[0:1] op_sel_hi:[1,0]
	s_waitcnt vmcnt(2)
	v_mov_b32_e32 v23, v26
	v_mov_b32_e32 v76, v27
	s_nop 0
	v_permlane32_swap_b32_e32 v24, v23
	v_permlane32_swap_b32_e32 v25, v76
	s_waitcnt vmcnt(1)
	v_pk_mul_f32 v[26:27], v[44:45], v[28:29]
	v_pk_mul_f32 v[28:29], v[46:47], v[30:31]
	s_waitcnt vmcnt(0)
; DI u32 pk2(float a, float b) { f2_t v = {a, b}; bf2_t r = __builtin_convertvector(v, bf2_t); return __builtin_bit_cast(u32, r); }
; DI float bflo(u32 u) { return __uint_as_float(u << 16); }
; DI float bfhi(u32 u) { return __uint_as_float(u & 0xffff0000u); }
; template <bool DIFF>
; DI void attn_phase(const AttnArgs& a, char* lds) {
;     ...
; #pragma unroll
;         for (int m = 0; m < NM; ++m)
; #pragma unroll
;           for (int bp = 0; bp < 2; ++bp) {
;             u32x2 pk[2];
;             const u32x4 gl = *(const u32x4*)(a.gate + go2 + 32 * m + 16 * bp);
;             const auto q0 = __builtin_amdgcn_permlane32_swap(gl[0], gl[2], false, false);
;             const auto q1 = __builtin_amdgcn_permlane32_swap(gl[1], gl[3], false, false);
;             u32x2 gsel[2]; gsel[0][0] = q0[0]; gsel[0][1] = q1[0]; gsel[1][0] = q0[1]; gsel[1][1] = q1[1];
; #pragma unroll
;             for (int bb = 0; bb < 2; ++bb) {
;               const int b = 2 * bp + bb;
;               const int dv = 32 * m + 8 * b;
;               const u32x2 gu = gsel[bb];
;               const float4 sg = *(const float4*)(a.subln + dv + 4 * g);
;               const float g0 = bflo(gu[0]), g1 = bfhi(gu[0]), g2 = bflo(gu[1]), g3 = bfhi(gu[1]);
;               const float y0 = o[m][4 * b] * rn * sg.x * g0 * __builtin_amdgcn_rcpf(1.f + __expf(-g0));
;               const float y1 = o[m][4 * b + 1] * rn * sg.y * g1 * __builtin_amdgcn_rcpf(1.f + __expf(-g1));
;               const float y2 = o[m][4 * b + 2] * rn * sg.z * g2 * __builtin_amdgcn_rcpf(1.f + __expf(-g2));
;               const float y3 = o[m][4 * b + 3] * rn * sg.w * g3 * __builtin_amdgcn_rcpf(1.f + __expf(-g3));
;               pk[bb][0] = pk2(y0, y1); pk[bb][1] = pk2(y2, y3);
;             }
;             const auto r0 = __builtin_amdgcn_permlane32_swap(pk[0][0], pk[1][0], false, false);
;             const auto r1 = __builtin_amdgcn_permlane32_swap(pk[0][1], pk[1][1], false, false);
;             u32x4 w; w[0] = r0[0]; w[1] = r1[0]; w[2] = r0[1]; w[3] = r1[1];
;             *(u32x4*)(a.og + oo2 + 32 * m + 16 * bp) = w;
;             __builtin_amdgcn_sched_barrier(0);
;           }
	v_pk_mul_f32 v[30:31], v[72:73], v[40:41]
	v_pk_mul_f32 v[40:41], v[74:75], v[42:43]
	v_lshlrev_b32_e32 v42, 16, v24
	v_and_b32_e32 v43, 0xffff0000, v24
	v_lshlrev_b32_e32 v24, 16, v25
	v_and_b32_e32 v25, 0xffff0000, v25
	v_lshlrev_b32_e32 v44, 16, v23
	v_and_b32_e32 v45, 0xffff0000, v23
	v_lshlrev_b32_e32 v46, 16, v76
	v_and_b32_e32 v47, 0xffff0000, v76
	v_mul_f32_e32 v23, 0xbfb8aa3b, v42
	v_pk_mul_f32 v[26:27], v[26:27], v[42:43]
	v_mul_f32_e32 v42, 0xbfb8aa3b, v43
	v_mul_f32_e32 v43, 0xbfb8aa3b, v24
	v_pk_mul_f32 v[28:29], v[28:29], v[24:25]
	v_mul_f32_e32 v72, 0xbfb8aa3b, v25
	v_mul_f32_e32 v73, 0xbfb8aa3b, v44
	v_pk_mul_f32 v[24:25], v[30:31], v[44:45]
	v_mul_f32_e32 v44, 0xbfb8aa3b, v45
	v_mul_f32_e32 v45, 0xbfb8aa3b, v46
	v_pk_mul_f32 v[30:31], v[40:41], v[46:47]
	v_mul_f32_e32 v40, 0xbfb8aa3b, v47
	v_exp_f32_e32 v23, v23
	v_exp_f32_e32 v41, v42
	v_exp_f32_e32 v42, v43
	v_exp_f32_e32 v43, v72
	v_exp_f32_e32 v46, v73
	v_exp_f32_e32 v44, v44
	v_exp_f32_e32 v45, v45
	v_exp_f32_e32 v40, v40
	v_add_f32_e32 v23, 1.0, v23
	v_add_f32_e32 v41, 1.0, v41
	v_add_f32_e32 v42, 1.0, v42
	v_add_f32_e32 v43, 1.0, v43
	v_add_f32_e32 v46, 1.0, v46
	v_add_f32_e32 v47, 1.0, v44
	v_add_f32_e32 v72, 1.0, v45
	v_add_f32_e32 v73, 1.0, v40
	v_rcp_f32_e32 v40, v23
	v_rcp_f32_e32 v41, v41
	v_rcp_f32_e32 v42, v42
	v_rcp_f32_e32 v43, v43
	v_rcp_f32_e32 v44, v46
	v_rcp_f32_e32 v45, v47
	v_rcp_f32_e32 v46, v72
	v_rcp_f32_e32 v47, v73
	v_pk_mul_f32 v[26:27], v[26:27], v[40:41]
	v_pk_mul_f32 v[28:29], v[28:29], v[42:43]
	v_pk_mul_f32 v[40:41], v[44:45], v[24:25]
	v_pk_mul_f32 v[30:31], v[46:47], v[30:31]
	v_cvt_pk_bf16_f32 v24, v26, v27
	v_cvt_pk_bf16_f32 v25, v28, v29
	v_cvt_pk_bf16_f32 v26, v40, v41
	v_cvt_pk_bf16_f32 v27, v30, v31
	s_nop 0
	v_permlane32_swap_b32_e32 v24, v26
	v_permlane32_swap_b32_e32 v25, v27
	global_store_dwordx4 v[14:15], v[24:27], off offset:288
	s_nop 0
	global_load_dwordx4 v[28:31], v22, s[46:47] offset:640
	global_load_dwordx4 v[40:43], v22, s[46:47] offset:672
	s_waitcnt vmcnt(17)
	v_mov_b32_e32 v24, v196
	v_mov_b32_e32 v25, v197
	v_mov_b32_e32 v26, v198
	v_mov_b32_e32 v27, v199
	v_pk_mul_f32 v[46:47], v[68:69], v[0:1] op_sel_hi:[1,0]
	v_pk_mul_f32 v[44:45], v[70:71], v[0:1] op_sel_hi:[1,0]
	v_pk_mul_f32 v[66:67], v[66:67], v[0:1] op_sel_hi:[1,0]
	v_pk_mul_f32 v[64:65], v[64:65], v[0:1] op_sel_hi:[1,0]
	s_waitcnt vmcnt(2)
	v_mov_b32_e32 v23, v26
	v_mov_b32_e32 v68, v27
	s_nop 0
	v_permlane32_swap_b32_e32 v24, v23
	v_permlane32_swap_b32_e32 v25, v68
	s_waitcnt vmcnt(1)
	v_pk_mul_f32 v[26:27], v[44:45], v[28:29]
	v_pk_mul_f32 v[28:29], v[46:47], v[30:31]
	s_waitcnt vmcnt(0)
	v_pk_mul_f32 v[30:31], v[66:67], v[40:41]
	v_pk_mul_f32 v[40:41], v[64:65], v[42:43]
	v_lshlrev_b32_e32 v42, 16, v24
	v_and_b32_e32 v43, 0xffff0000, v24
	v_lshlrev_b32_e32 v24, 16, v25
	v_and_b32_e32 v25, 0xffff0000, v25
	v_lshlrev_b32_e32 v44, 16, v23
	v_and_b32_e32 v45, 0xffff0000, v23
	v_lshlrev_b32_e32 v46, 16, v68
	v_and_b32_e32 v47, 0xffff0000, v68
	v_mul_f32_e32 v23, 0xbfb8aa3b, v42
	v_pk_mul_f32 v[26:27], v[26:27], v[42:43]
	v_mul_f32_e32 v42, 0xbfb8aa3b, v43
	v_mul_f32_e32 v43, 0xbfb8aa3b, v24
	v_pk_mul_f32 v[28:29], v[28:29], v[24:25]
	v_mul_f32_e32 v64, 0xbfb8aa3b, v25
	v_mul_f32_e32 v65, 0xbfb8aa3b, v44
	v_pk_mul_f32 v[24:25], v[30:31], v[44:45]
	v_mul_f32_e32 v44, 0xbfb8aa3b, v45
	v_mul_f32_e32 v45, 0xbfb8aa3b, v46
	v_pk_mul_f32 v[30:31], v[40:41], v[46:47]
	v_mul_f32_e32 v40, 0xbfb8aa3b, v47
	v_exp_f32_e32 v23, v23
	v_exp_f32_e32 v41, v42
	v_exp_f32_e32 v42, v43
	v_exp_f32_e32 v43, v64
	v_exp_f32_e32 v46, v65
	v_exp_f32_e32 v44, v44
	v_exp_f32_e32 v45, v45
	v_exp_f32_e32 v40, v40
	v_add_f32_e32 v23, 1.0, v23
	v_add_f32_e32 v41, 1.0, v41
	v_add_f32_e32 v42, 1.0, v42
	v_add_f32_e32 v43, 1.0, v43
	v_add_f32_e32 v46, 1.0, v46
	v_add_f32_e32 v47, 1.0, v44
	v_add_f32_e32 v64, 1.0, v45
	v_add_f32_e32 v65, 1.0, v40
	v_rcp_f32_e32 v40, v23
	v_rcp_f32_e32 v41, v41
	v_rcp_f32_e32 v42, v42
	v_rcp_f32_e32 v43, v43
	v_rcp_f32_e32 v44, v46
	v_rcp_f32_e32 v45, v47
	v_rcp_f32_e32 v46, v64
	v_rcp_f32_e32 v47, v65
	v_pk_mul_f32 v[26:27], v[26:27], v[40:41]
	v_pk_mul_f32 v[28:29], v[28:29], v[42:43]
	v_pk_mul_f32 v[40:41], v[44:45], v[24:25]
	v_pk_mul_f32 v[30:31], v[46:47], v[30:31]
	v_cvt_pk_bf16_f32 v24, v26, v27
	v_cvt_pk_bf16_f32 v25, v28, v29
	v_cvt_pk_bf16_f32 v26, v40, v41
	v_cvt_pk_bf16_f32 v27, v30, v31
	s_nop 0
	v_permlane32_swap_b32_e32 v24, v26
	v_permlane32_swap_b32_e32 v25, v27
	global_store_dwordx4 v[14:15], v[24:27], off offset:320
	s_nop 0
	global_load_dwordx4 v[28:31], v22, s[46:47] offset:704
	global_load_dwordx4 v[40:43], v22, s[46:47] offset:736
	s_waitcnt vmcnt(17)
	v_mov_b32_e32 v24, v200
	v_mov_b32_e32 v25, v201
	v_mov_b32_e32 v26, v202
	v_mov_b32_e32 v27, v203
	v_pk_mul_f32 v[44:45], v[56:57], v[0:1] op_sel_hi:[1,0]
	v_pk_mul_f32 v[56:57], v[60:61], v[0:1] op_sel_hi:[1,0]
	v_pk_mul_f32 v[46:47], v[58:59], v[0:1] op_sel_hi:[1,0]
	v_pk_mul_f32 v[58:59], v[62:63], v[0:1] op_sel_hi:[1,0]
	s_waitcnt vmcnt(2)
	v_mov_b32_e32 v23, v26
	v_mov_b32_e32 v60, v27
	s_nop 0
	v_permlane32_swap_b32_e32 v24, v23
	v_permlane32_swap_b32_e32 v25, v60
	s_waitcnt vmcnt(1)
	v_pk_mul_f32 v[26:27], v[44:45], v[28:29]
	v_pk_mul_f32 v[28:29], v[46:47], v[30:31]
	s_waitcnt vmcnt(0)
; DI u32 pk2(float a, float b) { f2_t v = {a, b}; bf2_t r = __builtin_convertvector(v, bf2_t); return __builtin_bit_cast(u32, r); }
; DI float bflo(u32 u) { return __uint_as_float(u << 16); }
; DI float bfhi(u32 u) { return __uint_as_float(u & 0xffff0000u); }
; template <bool DIFF>
; DI void attn_phase(const AttnArgs& a, char* lds) {
;     ...
; #pragma unroll
;         for (int m = 0; m < NM; ++m)
; #pragma unroll
;           for (int bp = 0; bp < 2; ++bp) {
;             u32x2 pk[2];
;             const u32x4 gl = *(const u32x4*)(a.gate + go2 + 32 * m + 16 * bp);
;             const auto q0 = __builtin_amdgcn_permlane32_swap(gl[0], gl[2], false, false);
;             const auto q1 = __builtin_amdgcn_permlane32_swap(gl[1], gl[3], false, false);
;             u32x2 gsel[2]; gsel[0][0] = q0[0]; gsel[0][1] = q1[0]; gsel[1][0] = q0[1]; gsel[1][1] = q1[1];
; #pragma unroll
;             for (int bb = 0; bb < 2; ++bb) {
;               const int b = 2 * bp + bb;
;               const int dv = 32 * m + 8 * b;
;               const u32x2 gu = gsel[bb];
;               const float4 sg = *(const float4*)(a.subln + dv + 4 * g);
;               const float g0 = bflo(gu[0]), g1 = bfhi(gu[0]), g2 = bflo(gu[1]), g3 = bfhi(gu[1]);
;               const float y0 = o[m][4 * b] * rn * sg.x * g0 * __builtin_amdgcn_rcpf(1.f + __expf(-g0));
;               const float y1 = o[m][4 * b + 1] * rn * sg.y * g1 * __builtin_amdgcn_rcpf(1.f + __expf(-g1));
;               const float y2 = o[m][4 * b + 2] * rn * sg.z * g2 * __builtin_amdgcn_rcpf(1.f + __expf(-g2));
;               const float y3 = o[m][4 * b + 3] * rn * sg.w * g3 * __builtin_amdgcn_rcpf(1.f + __expf(-g3));
;               pk[bb][0] = pk2(y0, y1); pk[bb][1] = pk2(y2, y3);
;             }
;             const auto r0 = __builtin_amdgcn_permlane32_swap(pk[0][0], pk[1][0], false, false);
;             const auto r1 = __builtin_amdgcn_permlane32_swap(pk[0][1], pk[1][1], false, false);
;             u32x4 w; w[0] = r0[0]; w[1] = r1[0]; w[2] = r0[1]; w[3] = r1[1];
;             *(u32x4*)(a.og + oo2 + 32 * m + 16 * bp) = w;
;             __builtin_amdgcn_sched_barrier(0);
;           }
	v_pk_mul_f32 v[30:31], v[56:57], v[40:41]
	v_pk_mul_f32 v[40:41], v[58:59], v[42:43]
	v_lshlrev_b32_e32 v42, 16, v24
	v_and_b32_e32 v43, 0xffff0000, v24
	v_lshlrev_b32_e32 v24, 16, v25
	v_and_b32_e32 v25, 0xffff0000, v25
	v_lshlrev_b32_e32 v44, 16, v23
	v_and_b32_e32 v45, 0xffff0000, v23
	v_lshlrev_b32_e32 v46, 16, v60
	v_and_b32_e32 v47, 0xffff0000, v60
	v_mul_f32_e32 v23, 0xbfb8aa3b, v42
	v_pk_mul_f32 v[26:27], v[26:27], v[42:43]
	v_mul_f32_e32 v42, 0xbfb8aa3b, v43
	v_mul_f32_e32 v43, 0xbfb8aa3b, v24
	v_pk_mul_f32 v[28:29], v[28:29], v[24:25]
	v_mul_f32_e32 v56, 0xbfb8aa3b, v25
	v_mul_f32_e32 v57, 0xbfb8aa3b, v44
	v_pk_mul_f32 v[24:25], v[30:31], v[44:45]
	v_mul_f32_e32 v44, 0xbfb8aa3b, v45
	v_mul_f32_e32 v45, 0xbfb8aa3b, v46
	v_pk_mul_f32 v[30:31], v[40:41], v[46:47]
	v_mul_f32_e32 v40, 0xbfb8aa3b, v47
	v_exp_f32_e32 v23, v23
	v_exp_f32_e32 v41, v42
	v_exp_f32_e32 v42, v43
	v_exp_f32_e32 v43, v56
	v_exp_f32_e32 v46, v57
	v_exp_f32_e32 v44, v44
	v_exp_f32_e32 v45, v45
	v_exp_f32_e32 v40, v40
	v_add_f32_e32 v23, 1.0, v23
	v_add_f32_e32 v41, 1.0, v41
	v_add_f32_e32 v42, 1.0, v42
	v_add_f32_e32 v43, 1.0, v43
	v_add_f32_e32 v46, 1.0, v46
	v_add_f32_e32 v47, 1.0, v44
	v_add_f32_e32 v56, 1.0, v45
	v_add_f32_e32 v57, 1.0, v40
	v_rcp_f32_e32 v40, v23
	v_rcp_f32_e32 v41, v41
	v_rcp_f32_e32 v42, v42
	v_rcp_f32_e32 v43, v43
	v_rcp_f32_e32 v44, v46
	v_rcp_f32_e32 v45, v47
	v_rcp_f32_e32 v46, v56
	v_rcp_f32_e32 v47, v57
	v_pk_mul_f32 v[26:27], v[26:27], v[40:41]
	v_pk_mul_f32 v[28:29], v[28:29], v[42:43]
	v_pk_mul_f32 v[40:41], v[44:45], v[24:25]
	v_pk_mul_f32 v[30:31], v[46:47], v[30:31]
	v_cvt_pk_bf16_f32 v24, v26, v27
	v_cvt_pk_bf16_f32 v25, v28, v29
	v_cvt_pk_bf16_f32 v26, v40, v41
	v_cvt_pk_bf16_f32 v27, v30, v31
	s_nop 0
	v_permlane32_swap_b32_e32 v24, v26
	v_permlane32_swap_b32_e32 v25, v27
	global_store_dwordx4 v[14:15], v[24:27], off offset:352
	s_nop 0
	global_load_dwordx4 v[28:31], v22, s[46:47] offset:768
	global_load_dwordx4 v[40:43], v22, s[46:47] offset:800
	s_waitcnt vmcnt(17)
	v_mov_b32_e32 v24, v204
	v_mov_b32_e32 v25, v205
	v_mov_b32_e32 v26, v206
	v_mov_b32_e32 v27, v207
	v_pk_mul_f32 v[46:47], v[52:53], v[0:1] op_sel_hi:[1,0]
	v_pk_mul_f32 v[44:45], v[54:55], v[0:1] op_sel_hi:[1,0]
	v_pk_mul_f32 v[50:51], v[50:51], v[0:1] op_sel_hi:[1,0]
	v_pk_mul_f32 v[48:49], v[48:49], v[0:1] op_sel_hi:[1,0]
	s_waitcnt vmcnt(2)
	v_mov_b32_e32 v23, v26
	v_mov_b32_e32 v52, v27
	s_nop 0
	v_permlane32_swap_b32_e32 v24, v23
	v_permlane32_swap_b32_e32 v25, v52
	s_waitcnt vmcnt(1)
	v_pk_mul_f32 v[26:27], v[44:45], v[28:29]
	v_pk_mul_f32 v[28:29], v[46:47], v[30:31]
	s_waitcnt vmcnt(0)
	v_pk_mul_f32 v[30:31], v[50:51], v[40:41]
	v_pk_mul_f32 v[40:41], v[48:49], v[42:43]
	v_lshlrev_b32_e32 v42, 16, v24
	v_and_b32_e32 v43, 0xffff0000, v24
	v_lshlrev_b32_e32 v24, 16, v25
	v_and_b32_e32 v25, 0xffff0000, v25
	v_lshlrev_b32_e32 v44, 16, v23
	v_and_b32_e32 v45, 0xffff0000, v23
	v_lshlrev_b32_e32 v46, 16, v52
	v_and_b32_e32 v47, 0xffff0000, v52
	v_mul_f32_e32 v23, 0xbfb8aa3b, v42
	v_pk_mul_f32 v[26:27], v[26:27], v[42:43]
	v_mul_f32_e32 v42, 0xbfb8aa3b, v43
	v_mul_f32_e32 v43, 0xbfb8aa3b, v24
	v_pk_mul_f32 v[28:29], v[28:29], v[24:25]
	v_mul_f32_e32 v48, 0xbfb8aa3b, v25
	v_mul_f32_e32 v49, 0xbfb8aa3b, v44
	v_pk_mul_f32 v[24:25], v[30:31], v[44:45]
	v_mul_f32_e32 v44, 0xbfb8aa3b, v45
	v_mul_f32_e32 v45, 0xbfb8aa3b, v46
	v_pk_mul_f32 v[30:31], v[40:41], v[46:47]
	v_mul_f32_e32 v40, 0xbfb8aa3b, v47
	v_exp_f32_e32 v23, v23
	v_exp_f32_e32 v41, v42
	v_exp_f32_e32 v42, v43
	v_exp_f32_e32 v43, v48
	v_exp_f32_e32 v46, v49
	v_exp_f32_e32 v44, v44
	v_exp_f32_e32 v45, v45
	v_exp_f32_e32 v40, v40
	v_add_f32_e32 v23, 1.0, v23
	v_add_f32_e32 v41, 1.0, v41
	v_add_f32_e32 v42, 1.0, v42
	v_add_f32_e32 v43, 1.0, v43
	v_add_f32_e32 v46, 1.0, v46
	v_add_f32_e32 v47, 1.0, v44
	v_add_f32_e32 v48, 1.0, v45
	v_add_f32_e32 v49, 1.0, v40
	v_rcp_f32_e32 v40, v23
	v_rcp_f32_e32 v41, v41
	v_rcp_f32_e32 v42, v42
	v_rcp_f32_e32 v43, v43
	v_rcp_f32_e32 v44, v46
	v_rcp_f32_e32 v45, v47
	v_rcp_f32_e32 v46, v48
	v_rcp_f32_e32 v47, v49
	v_pk_mul_f32 v[26:27], v[26:27], v[40:41]
	v_pk_mul_f32 v[28:29], v[28:29], v[42:43]
	v_pk_mul_f32 v[40:41], v[44:45], v[24:25]
	v_pk_mul_f32 v[30:31], v[46:47], v[30:31]
	v_cvt_pk_bf16_f32 v24, v26, v27
	v_cvt_pk_bf16_f32 v25, v28, v29
	v_cvt_pk_bf16_f32 v26, v40, v41
	v_cvt_pk_bf16_f32 v27, v30, v31
	s_nop 0
	v_permlane32_swap_b32_e32 v24, v26
	v_permlane32_swap_b32_e32 v25, v27
	global_store_dwordx4 v[14:15], v[24:27], off offset:384
	s_nop 0
	global_load_dwordx4 v[28:31], v22, s[46:47] offset:832
	global_load_dwordx4 v[40:43], v22, s[46:47] offset:864
	s_waitcnt vmcnt(17)
	v_mov_b32_e32 v24, v228
	v_mov_b32_e32 v25, v229
	v_mov_b32_e32 v26, v230
	v_mov_b32_e32 v27, v231
	v_pk_mul_f32 v[38:39], v[38:39], v[0:1] op_sel_hi:[1,0]
	v_pk_mul_f32 v[36:37], v[36:37], v[0:1] op_sel_hi:[1,0]
	v_pk_mul_f32 v[34:35], v[34:35], v[0:1] op_sel_hi:[1,0]
	v_pk_mul_f32 v[32:33], v[32:33], v[0:1] op_sel_hi:[1,0]
	s_waitcnt vmcnt(2)
	v_mov_b32_e32 v23, v26
	v_mov_b32_e32 v44, v27
	s_nop 0
	v_permlane32_swap_b32_e32 v24, v23
	v_permlane32_swap_b32_e32 v25, v44
	s_waitcnt vmcnt(1)
	v_pk_mul_f32 v[26:27], v[38:39], v[28:29]
	v_pk_mul_f32 v[28:29], v[36:37], v[30:31]
	s_waitcnt vmcnt(0)
; DI u32 pk2(float a, float b) { f2_t v = {a, b}; bf2_t r = __builtin_convertvector(v, bf2_t); return __builtin_bit_cast(u32, r); }
; DI float bflo(u32 u) { return __uint_as_float(u << 16); }
; DI float bfhi(u32 u) { return __uint_as_float(u & 0xffff0000u); }
; template <bool DIFF>
; DI void attn_phase(const AttnArgs& a, char* lds) {
;     ...
; #pragma unroll
;         for (int m = 0; m < NM; ++m)
; #pragma unroll
;           for (int bp = 0; bp < 2; ++bp) {
;             u32x2 pk[2];
;             const u32x4 gl = *(const u32x4*)(a.gate + go2 + 32 * m + 16 * bp);
;             const auto q0 = __builtin_amdgcn_permlane32_swap(gl[0], gl[2], false, false);
;             const auto q1 = __builtin_amdgcn_permlane32_swap(gl[1], gl[3], false, false);
;             u32x2 gsel[2]; gsel[0][0] = q0[0]; gsel[0][1] = q1[0]; gsel[1][0] = q0[1]; gsel[1][1] = q1[1];
; #pragma unroll
;             for (int bb = 0; bb < 2; ++bb) {
;               const int b = 2 * bp + bb;
;               const int dv = 32 * m + 8 * b;
;               const u32x2 gu = gsel[bb];
;               const float4 sg = *(const float4*)(a.subln + dv + 4 * g);
;               const float g0 = bflo(gu[0]), g1 = bfhi(gu[0]), g2 = bflo(gu[1]), g3 = bfhi(gu[1]);
;               const float y0 = o[m][4 * b] * rn * sg.x * g0 * __builtin_amdgcn_rcpf(1.f + __expf(-g0));
;               const float y1 = o[m][4 * b + 1] * rn * sg.y * g1 * __builtin_amdgcn_rcpf(1.f + __expf(-g1));
;               const float y2 = o[m][4 * b + 2] * rn * sg.z * g2 * __builtin_amdgcn_rcpf(1.f + __expf(-g2));
;               const float y3 = o[m][4 * b + 3] * rn * sg.w * g3 * __builtin_amdgcn_rcpf(1.f + __expf(-g3));
;               pk[bb][0] = pk2(y0, y1); pk[bb][1] = pk2(y2, y3);
;             }
;             const auto r0 = __builtin_amdgcn_permlane32_swap(pk[0][0], pk[1][0], false, false);
;             const auto r1 = __builtin_amdgcn_permlane32_swap(pk[0][1], pk[1][1], false, false);
;             u32x4 w; w[0] = r0[0]; w[1] = r1[0]; w[2] = r0[1]; w[3] = r1[1];
;             *(u32x4*)(a.og + oo2 + 32 * m + 16 * bp) = w;
;             __builtin_amdgcn_sched_barrier(0);
;           }
	v_pk_mul_f32 v[30:31], v[34:35], v[40:41]
	v_pk_mul_f32 v[32:33], v[32:33], v[42:43]
	v_lshlrev_b32_e32 v34, 16, v24
	v_and_b32_e32 v35, 0xffff0000, v24
	v_lshlrev_b32_e32 v24, 16, v25
	v_and_b32_e32 v25, 0xffff0000, v25
	v_lshlrev_b32_e32 v36, 16, v23
	v_and_b32_e32 v37, 0xffff0000, v23
	v_lshlrev_b32_e32 v38, 16, v44
	v_and_b32_e32 v39, 0xffff0000, v44
	v_mul_f32_e32 v23, 0xbfb8aa3b, v34
	v_pk_mul_f32 v[26:27], v[26:27], v[34:35]
	v_mul_f32_e32 v34, 0xbfb8aa3b, v35
	v_mul_f32_e32 v35, 0xbfb8aa3b, v24
	v_pk_mul_f32 v[28:29], v[28:29], v[24:25]
	v_mul_f32_e32 v40, 0xbfb8aa3b, v25
	v_mul_f32_e32 v41, 0xbfb8aa3b, v36
	v_pk_mul_f32 v[24:25], v[30:31], v[36:37]
	v_mul_f32_e32 v36, 0xbfb8aa3b, v37
	v_mul_f32_e32 v37, 0xbfb8aa3b, v38
	v_pk_mul_f32 v[30:31], v[32:33], v[38:39]
	v_mul_f32_e32 v32, 0xbfb8aa3b, v39
	v_exp_f32_e32 v23, v23
	v_exp_f32_e32 v33, v34
	v_exp_f32_e32 v34, v35
	v_exp_f32_e32 v35, v40
	v_exp_f32_e32 v38, v41
	v_exp_f32_e32 v36, v36
	v_exp_f32_e32 v37, v37
	v_exp_f32_e32 v32, v32
	v_add_f32_e32 v23, 1.0, v23
	v_add_f32_e32 v33, 1.0, v33
	v_add_f32_e32 v34, 1.0, v34
	v_add_f32_e32 v35, 1.0, v35
	v_add_f32_e32 v38, 1.0, v38
	v_add_f32_e32 v39, 1.0, v36
	v_add_f32_e32 v40, 1.0, v37
	v_add_f32_e32 v41, 1.0, v32
	v_rcp_f32_e32 v32, v23
	v_rcp_f32_e32 v33, v33
	v_rcp_f32_e32 v34, v34
	v_rcp_f32_e32 v35, v35
	v_rcp_f32_e32 v36, v38
	v_rcp_f32_e32 v37, v39
	v_rcp_f32_e32 v38, v40
	v_rcp_f32_e32 v39, v41
	v_pk_mul_f32 v[26:27], v[26:27], v[32:33]
	v_pk_mul_f32 v[28:29], v[28:29], v[34:35]
	v_pk_mul_f32 v[32:33], v[36:37], v[24:25]
	v_pk_mul_f32 v[30:31], v[38:39], v[30:31]
	v_cvt_pk_bf16_f32 v24, v26, v27
	v_cvt_pk_bf16_f32 v25, v28, v29
	v_cvt_pk_bf16_f32 v26, v32, v33
	v_cvt_pk_bf16_f32 v27, v30, v31
	s_nop 0
	v_permlane32_swap_b32_e32 v24, v26
	v_permlane32_swap_b32_e32 v25, v27
	global_store_dwordx4 v[14:15], v[24:27], off offset:416
	s_nop 0
	global_load_dwordx4 v[28:31], v22, s[46:47] offset:896
	global_load_dwordx4 v[32:35], v22, s[46:47] offset:928
	s_waitcnt vmcnt(17)
	v_mov_b32_e32 v24, v232
	v_mov_b32_e32 v25, v233
	v_mov_b32_e32 v26, v234
	v_mov_b32_e32 v27, v235
	v_pk_mul_f32 v[16:17], v[16:17], v[0:1] op_sel_hi:[1,0]
	v_pk_mul_f32 v[18:19], v[18:19], v[0:1] op_sel_hi:[1,0]
	v_pk_mul_f32 v[20:21], v[20:21], v[0:1] op_sel_hi:[1,0]
	v_pk_mul_f32 v[10:11], v[10:11], v[0:1] op_sel_hi:[1,0]
	s_waitcnt vmcnt(2)
	v_mov_b32_e32 v23, v26
	v_mov_b32_e32 v36, v27
	s_nop 0
	v_permlane32_swap_b32_e32 v24, v23
	v_permlane32_swap_b32_e32 v25, v36
	s_waitcnt vmcnt(1)
	v_pk_mul_f32 v[16:17], v[16:17], v[28:29]
	v_pk_mul_f32 v[18:19], v[18:19], v[30:31]
	s_waitcnt vmcnt(0)
; DI u32 pk2(float a, float b) { f2_t v = {a, b}; bf2_t r = __builtin_convertvector(v, bf2_t); return __builtin_bit_cast(u32, r); }
; DI float bflo(u32 u) { return __uint_as_float(u << 16); }
; DI float bfhi(u32 u) { return __uint_as_float(u & 0xffff0000u); }
; template <bool DIFF>
; DI void attn_phase(const AttnArgs& a, char* lds) {
;     ...
; #pragma unroll
;         for (int m = 0; m < NM; ++m)
; #pragma unroll
;           for (int bp = 0; bp < 2; ++bp) {
;             u32x2 pk[2];
;             const u32x4 gl = *(const u32x4*)(a.gate + go2 + 32 * m + 16 * bp);
;             const auto q0 = __builtin_amdgcn_permlane32_swap(gl[0], gl[2], false, false);
;             const auto q1 = __builtin_amdgcn_permlane32_swap(gl[1], gl[3], false, false);
;             u32x2 gsel[2]; gsel[0][0] = q0[0]; gsel[0][1] = q1[0]; gsel[1][0] = q0[1]; gsel[1][1] = q1[1];
; #pragma unroll
;             for (int bb = 0; bb < 2; ++bb) {
;               const int b = 2 * bp + bb;
;               const int dv = 32 * m + 8 * b;
;               const u32x2 gu = gsel[bb];
;               const float4 sg = *(const float4*)(a.subln + dv + 4 * g);
;               const float g0 = bflo(gu[0]), g1 = bfhi(gu[0]), g2 = bflo(gu[1]), g3 = bfhi(gu[1]);
;               const float y0 = o[m][4 * b] * rn * sg.x * g0 * __builtin_amdgcn_rcpf(1.f + __expf(-g0));
;               const float y1 = o[m][4 * b + 1] * rn * sg.y * g1 * __builtin_amdgcn_rcpf(1.f + __expf(-g1));
;               const float y2 = o[m][4 * b + 2] * rn * sg.z * g2 * __builtin_amdgcn_rcpf(1.f + __expf(-g2));
;               const float y3 = o[m][4 * b + 3] * rn * sg.w * g3 * __builtin_amdgcn_rcpf(1.f + __expf(-g3));
;               pk[bb][0] = pk2(y0, y1); pk[bb][1] = pk2(y2, y3);
;             }
;             const auto r0 = __builtin_amdgcn_permlane32_swap(pk[0][0], pk[1][0], false, false);
;             const auto r1 = __builtin_amdgcn_permlane32_swap(pk[0][1], pk[1][1], false, false);
;             u32x4 w; w[0] = r0[0]; w[1] = r1[0]; w[2] = r0[1]; w[3] = r1[1];
;             *(u32x4*)(a.og + oo2 + 32 * m + 16 * bp) = w;
;             __builtin_amdgcn_sched_barrier(0);
;           }
;       }
;       __syncthreads();
	v_pk_mul_f32 v[20:21], v[20:21], v[32:33]
	v_pk_mul_f32 v[10:11], v[10:11], v[34:35]
	v_lshlrev_b32_e32 v26, 16, v24
	v_and_b32_e32 v27, 0xffff0000, v24
	v_lshlrev_b32_e32 v24, 16, v25
	v_and_b32_e32 v25, 0xffff0000, v25
	v_lshlrev_b32_e32 v28, 16, v23
	v_and_b32_e32 v29, 0xffff0000, v23
	v_lshlrev_b32_e32 v30, 16, v36
	v_and_b32_e32 v31, 0xffff0000, v36
	v_mul_f32_e32 v23, 0xbfb8aa3b, v26
	v_pk_mul_f32 v[16:17], v[16:17], v[26:27]
	v_mul_f32_e32 v26, 0xbfb8aa3b, v27
	v_mul_f32_e32 v27, 0xbfb8aa3b, v24
	v_pk_mul_f32 v[18:19], v[18:19], v[24:25]
	v_mul_f32_e32 v24, 0xbfb8aa3b, v25
	v_mul_f32_e32 v25, 0xbfb8aa3b, v28
	v_pk_mul_f32 v[20:21], v[20:21], v[28:29]
	v_mul_f32_e32 v28, 0xbfb8aa3b, v29
	v_mul_f32_e32 v29, 0xbfb8aa3b, v30
	v_pk_mul_f32 v[10:11], v[10:11], v[30:31]
	v_mul_f32_e32 v30, 0xbfb8aa3b, v31
	v_exp_f32_e32 v23, v23
	v_exp_f32_e32 v26, v26
	v_exp_f32_e32 v27, v27
	v_exp_f32_e32 v24, v24
	v_exp_f32_e32 v25, v25
	v_exp_f32_e32 v28, v28
	v_exp_f32_e32 v29, v29
	v_exp_f32_e32 v30, v30
	v_add_f32_e32 v23, 1.0, v23
	v_add_f32_e32 v26, 1.0, v26
	v_add_f32_e32 v27, 1.0, v27
	v_add_f32_e32 v31, 1.0, v24
	v_add_f32_e32 v32, 1.0, v25
	v_add_f32_e32 v33, 1.0, v28
	v_add_f32_e32 v34, 1.0, v29
	v_add_f32_e32 v35, 1.0, v30
	v_rcp_f32_e32 v24, v23
	v_rcp_f32_e32 v25, v26
	v_rcp_f32_e32 v26, v27
	v_rcp_f32_e32 v27, v31
	v_rcp_f32_e32 v28, v32
	v_rcp_f32_e32 v29, v33
	v_rcp_f32_e32 v30, v34
	v_rcp_f32_e32 v31, v35
	v_pk_mul_f32 v[16:17], v[16:17], v[24:25]
	v_pk_mul_f32 v[18:19], v[18:19], v[26:27]
	v_pk_mul_f32 v[20:21], v[28:29], v[20:21]
	v_pk_mul_f32 v[10:11], v[30:31], v[10:11]
	v_cvt_pk_bf16_f32 v16, v16, v17
	v_cvt_pk_bf16_f32 v17, v18, v19
	v_cvt_pk_bf16_f32 v18, v20, v21
	v_cvt_pk_bf16_f32 v19, v10, v11
	s_nop 0
	v_permlane32_swap_b32_e32 v16, v18
	v_permlane32_swap_b32_e32 v17, v19
	global_store_dwordx4 v[14:15], v[16:19], off offset:448
	s_nop 0
	global_load_dwordx4 v[16:19], v22, s[46:47] offset:960
	s_nop 0
	global_load_dwordx4 v[20:23], v22, s[46:47] offset:992
	s_waitcnt vmcnt(17)
	v_mov_b32_e32 v10, v236
	v_mov_b32_e32 v11, v237
	v_mov_b32_e32 v12, v238
	v_mov_b32_e32 v13, v239
	v_pk_mul_f32 v[8:9], v[8:9], v[0:1] op_sel_hi:[1,0]
	v_pk_mul_f32 v[6:7], v[6:7], v[0:1] op_sel_hi:[1,0]
	v_pk_mul_f32 v[4:5], v[4:5], v[0:1] op_sel_hi:[1,0]
	v_pk_mul_f32 v[2:3], v[2:3], v[0:1] op_sel_hi:[1,0]
	s_waitcnt vmcnt(2)
	v_mov_b32_e32 v0, v12
	v_mov_b32_e32 v24, v13
	s_nop 0
	v_permlane32_swap_b32_e32 v10, v0
	v_permlane32_swap_b32_e32 v11, v24
	s_waitcnt vmcnt(1)
	v_pk_mul_f32 v[8:9], v[8:9], v[16:17]
	v_pk_mul_f32 v[6:7], v[6:7], v[18:19]
	s_waitcnt vmcnt(0)
	v_pk_mul_f32 v[4:5], v[4:5], v[20:21]
	v_pk_mul_f32 v[2:3], v[2:3], v[22:23]
	v_lshlrev_b32_e32 v12, 16, v10
	v_and_b32_e32 v13, 0xffff0000, v10
	v_lshlrev_b32_e32 v10, 16, v11
	v_and_b32_e32 v11, 0xffff0000, v11
	v_lshlrev_b32_e32 v16, 16, v0
	v_and_b32_e32 v17, 0xffff0000, v0
	v_lshlrev_b32_e32 v18, 16, v24
	v_and_b32_e32 v19, 0xffff0000, v24
	v_mul_f32_e32 v0, 0xbfb8aa3b, v12
	v_pk_mul_f32 v[8:9], v[8:9], v[12:13]
	v_mul_f32_e32 v12, 0xbfb8aa3b, v13
	v_mul_f32_e32 v13, 0xbfb8aa3b, v10
	v_pk_mul_f32 v[6:7], v[6:7], v[10:11]
	v_mul_f32_e32 v10, 0xbfb8aa3b, v11
	v_mul_f32_e32 v11, 0xbfb8aa3b, v16
	v_pk_mul_f32 v[4:5], v[4:5], v[16:17]
	v_mul_f32_e32 v16, 0xbfb8aa3b, v17
	v_mul_f32_e32 v17, 0xbfb8aa3b, v18
	v_pk_mul_f32 v[2:3], v[2:3], v[18:19]
	v_mul_f32_e32 v18, 0xbfb8aa3b, v19
	v_exp_f32_e32 v0, v0
	v_exp_f32_e32 v12, v12
	v_exp_f32_e32 v13, v13
	v_exp_f32_e32 v10, v10
	v_exp_f32_e32 v11, v11
	v_exp_f32_e32 v16, v16
	v_exp_f32_e32 v17, v17
	v_exp_f32_e32 v18, v18
	v_add_f32_e32 v0, 1.0, v0
	v_add_f32_e32 v12, 1.0, v12
	v_add_f32_e32 v13, 1.0, v13
	v_add_f32_e32 v19, 1.0, v10
	v_add_f32_e32 v20, 1.0, v11
	v_add_f32_e32 v21, 1.0, v16
	v_add_f32_e32 v22, 1.0, v17
	v_add_f32_e32 v23, 1.0, v18
	v_rcp_f32_e32 v10, v0
	v_rcp_f32_e32 v11, v12
	v_rcp_f32_e32 v12, v13
	v_rcp_f32_e32 v13, v19
	v_rcp_f32_e32 v16, v20
	v_rcp_f32_e32 v17, v21
	v_rcp_f32_e32 v18, v22
	v_rcp_f32_e32 v19, v23
	v_pk_mul_f32 v[8:9], v[8:9], v[10:11]
	v_pk_mul_f32 v[6:7], v[6:7], v[12:13]
	v_pk_mul_f32 v[4:5], v[16:17], v[4:5]
	v_pk_mul_f32 v[10:11], v[18:19], v[2:3]
	v_cvt_pk_bf16_f32 v2, v8, v9
	v_cvt_pk_bf16_f32 v3, v6, v7
	v_cvt_pk_bf16_f32 v4, v4, v5
	v_cvt_pk_bf16_f32 v5, v10, v11
	s_nop 0
	v_permlane32_swap_b32_e32 v2, v4
	v_permlane32_swap_b32_e32 v3, v5
	global_store_dwordx4 v[14:15], v[2:5], off offset:480
	s_branch .LBB0_587
